# norm1: all four token rows of a wave prefetched at item start
# baseline (speedup 1.0000x reference)
; template <int WHICH>
; DI void norm_item(const CP& p, int l, int item) {
;     ...
;   if (WHICH == 1 && item == 0 && tid < 8) p.kmax[tid] = 0u;
;   if (WHICH == 1 && tid < 32) p.rowss[item * 32 + tid] = 0.f;
; #pragma unroll
;   for (int it = 0; it < 4; ++it) {
;     const int t = item * 32 + w * 4 + it;
;     const int b = t / S_;
;     fl4 xv[4];
;     float ssq = 0.f;
; #pragma unroll
;     for (int q = 0; q < 4; ++q) {
;       xv[q] = *(const fl4*)(xs + (size_t)t * 1024 + q * 256 + lane * 4);
;       ssq += xv[q].x * xv[q].x + xv[q].y * xv[q].y + xv[q].z * xv[q].z + xv[q].w * xv[q].w;
;     }
;     ssq = wave_sum(ssq);
;     const float rstd = __builtin_amdgcn_rsqf(ssq * (1.f / 1024.f) + 1e-6f);
;     if (WHICH == 3) {
; #pragma unroll
;       for (int q = 0; q < 4; ++q) {
;         fl4 g = *(const fl4*)(gain + q * 256 + lane * 4);
;         fl4 o;
;         o.x = xv[q].x * rstd * g.x; o.y = xv[q].y * rstd * g.y; o.z = xv[q].z * rstd * g.z; o.w = xv[q].w * rstd * g.w;
;         *(fl4*)(p.out + (size_t)t * 1024 + q * 256 + lane * 4) = o;
;       }
;     } else {
;       const float* md = p.mod + ((size_t)l * 2 + b) * 6144 + (WHICH == 1 ? 0 : 3072);
;       float f0 = 0.f, f1 = 0.f, f2 = 0.f, f3 = 0.f;
; #pragma unroll
;       for (int q = 0; q < 4; ++q) {
;         const int col = q * 256 + lane * 4;
;         fl4 g = *(const fl4*)(gain + col);
;         fl4 sh = *(const fl4*)(md + col);
;         fl4 sc = *(const fl4*)(md + 1024 + col);
;         fl4 h;
;         h.x = xv[q].x * rstd * g.x * (1.f + sc.x) + sh.x;
;         h.y = xv[q].y * rstd * g.y * (1.f + sc.y) + sh.y;
;         h.z = xv[q].z * rstd * g.z * (1.f + sc.z) + sh.z;
;         h.w = xv[q].w * rstd * g.w * (1.f + sc.w) + sh.w;
;         u32x2 v;
;         v.x = pk2(h.x, h.y); v.y = pk2(h.z, h.w);
;         *(u32x2*)(p.hbuf + (size_t)t * 1024 + col) = v;
;         if (WHICH == 1) {
;           const float* wf = p.wf + (size_t)l * 4096 + col;
;           fl4 w0 = *(const fl4*)(wf), w1 = *(const fl4*)(wf + 1024), w2 = *(const fl4*)(wf + 2048), w3 = *(const fl4*)(wf + 3072);
;           f0 += h.x * w0.x + h.y * w0.y + h.z * w0.z + h.w * w0.w;
;           f1 += h.x * w1.x + h.y * w1.y + h.z * w1.z + h.w * w1.w;
;           f2 += h.x * w2.x + h.y * w2.y + h.z * w2.z + h.w * w2.w;
;           f3 += h.x * w3.x + h.y * w3.y + h.z * w3.z + h.w * w3.w;
.LBB0_631:
	s_or_b64 exec, exec, s[6:7]
	v_and_b32_e32 v117, 63, v0
	v_ashrrev_i32_e32 v0, 4, v0
	v_and_b32_e32 v92, -4, v0
	v_add_u32_e32 v66, s69, v92
	v_lshlrev_b32_e32 v32, 4, v117
	v_ashrrev_i32_e32 v67, 31, v66
	s_waitcnt lgkmcnt(0)
	v_lshl_add_u64 v[70:71], s[4:5], 0, v[32:33]
	v_lshlrev_b64 v[0:1], 12, v[66:67]
	v_lshl_add_u64 v[0:1], v[70:71], 0, v[0:1]
	global_load_dwordx4 v[12:15], v[0:1], off
	global_load_dwordx4 v[8:11], v[0:1], off offset:1024
	global_load_dwordx4 v[4:7], v[0:1], off offset:2048
	s_nop 0
	v_lshl_add_u64 v[232:233], v[0:1], 0, s[60:61]
	v_lshl_add_u64 v[234:235], v[232:233], 0, s[60:61]
	v_lshl_add_u64 v[236:237], v[234:235], 0, s[60:61]
	global_load_dwordx4 v[0:3], v[0:1], off offset:3072
	global_load_dwordx4 v[168:171], v[232:233], off
	global_load_dwordx4 v[172:175], v[232:233], off offset:1024
	global_load_dwordx4 v[176:179], v[232:233], off offset:2048
	global_load_dwordx4 v[180:183], v[232:233], off offset:3072
	global_load_dwordx4 v[184:187], v[234:235], off
	global_load_dwordx4 v[188:191], v[234:235], off offset:1024
	global_load_dwordx4 v[192:195], v[234:235], off offset:2048
	global_load_dwordx4 v[196:199], v[234:235], off offset:3072
	global_load_dwordx4 v[216:219], v[236:237], off
	global_load_dwordx4 v[220:223], v[236:237], off offset:1024
	global_load_dwordx4 v[224:227], v[236:237], off offset:2048
	global_load_dwordx4 v[228:231], v[236:237], off offset:3072
	v_lshrrev_b32_e32 v18, 18, v67
	v_add_u32_e32 v18, v66, v18
	v_ashrrev_i32_e32 v54, 14, v18
	v_ashrrev_i32_e32 v55, 31, v54
	v_mov_b64_e32 v[16:17], s[14:15]
	v_lshl_add_u64 v[18:19], s[28:29], 0, v[54:55]
	v_mad_u64_u32 v[24:25], s[4:5], v18, s93, v[16:17]
	v_mad_i32_i24 v25, v19, s93, v25
	v_lshl_add_u64 v[26:27], v[24:25], 0, s[60:61]
	v_mov_b32_e32 v34, v202
	v_lshl_add_u64 v[16:17], v[26:27], 0, v[32:33]
	global_load_dwordx4 v[16:19], v[16:17], off
	s_nop 0
	global_load_dwordx4 v[20:23], v32, s[26:27]
	v_lshl_add_u64 v[24:25], v[24:25], 0, v[32:33]
	global_load_dwordx4 v[28:31], v[24:25], off
	v_lshlrev_b32_e32 v42, 2, v34
	v_bitop3_b32 v43, v42, s84, v211 bitop3:0x6c
	v_lshlrev_b32_e32 v63, 2, v117
	v_mov_b32_e32 v73, v33
	v_lshl_add_u64 v[68:69], s[12:13], 0, v[32:33]
	s_waitcnt vmcnt(0)
	v_add_co_u32_e32 v82, vcc, s89, v68
	v_mov_b32_e32 v75, v33
	s_nop 0
	v_addc_co_u32_e32 v83, vcc, 0, v69, vcc
	v_add_co_u32_e32 v84, vcc, s94, v68
	v_mov_b32_e32 v77, v33
	s_nop 0
	v_addc_co_u32_e32 v85, vcc, 0, v69, vcc
	v_add_co_u32_e32 v90, vcc, s42, v68
	v_mov_b32_e32 v93, v202
	s_nop 0
	v_addc_co_u32_e32 v91, vcc, 0, v69, vcc
	v_mov_b32_e32 v57, v33
	v_add_u32_e32 v56, s48, v117
	v_cmp_gt_u32_e64 s[4:5], 4, v117
	v_cmp_eq_u32_e32 vcc, 2, v117
	v_mul_f32_e32 v44, v13, v13
	v_mul_f32_e32 v45, v9, v9
	v_mov_b32_e32 v36, v5
	v_mov_b32_e32 v37, v1
	v_mov_b32_e32 v34, v4
	v_mov_b32_e32 v35, v0
	v_fmac_f32_e32 v44, v12, v12
	v_fmac_f32_e32 v45, v8, v8
	v_pk_mul_f32 v[36:37], v[36:37], v[36:37]
	v_mov_b32_e32 v38, v6
	v_mov_b32_e32 v39, v2
	v_fmac_f32_e32 v44, v14, v14
	v_fmac_f32_e32 v45, v10, v10
	v_pk_fma_f32 v[34:35], v[34:35], v[34:35], v[36:37]
	v_mov_b32_e32 v40, v7
	v_mov_b32_e32 v41, v3
	v_fmac_f32_e32 v44, v15, v15
	v_fmac_f32_e32 v45, v11, v11
	v_pk_fma_f32 v[34:35], v[38:39], v[38:39], v[34:35]
	v_add_f32_e32 v36, v44, v45
	v_pk_fma_f32 v[34:35], v[40:41], v[40:41], v[34:35]
	v_bitop3_b32 v37, v42, 8, v211 bitop3:0x6c
	v_add_f32_e32 v34, v36, v34
	v_add_f32_e32 v34, v34, v35
	ds_bpermute_b32 v35, v43, v34
	v_bitop3_b32 v36, v42, 64, v211 bitop3:0x6c
	v_bitop3_b32 v39, v42, 4, v211 bitop3:0x6c
	v_pk_add_f32 v[16:17], v[16:17], 1.0 op_sel_hi:[1,0]
	v_pk_add_f32 v[18:19], v[18:19], 1.0 op_sel_hi:[1,0]
	s_waitcnt lgkmcnt(0)
	v_add_f32_e32 v34, v34, v35
	ds_bpermute_b32 v35, v36, v34
	v_bitop3_b32 v36, v42, 32, v211 bitop3:0x6c
	v_or_b32_e32 v38, 0x100, v63
	v_lshlrev_b32_e32 v72, 2, v38
	s_waitcnt lgkmcnt(0)
	v_add_f32_e32 v34, v34, v35
	ds_bpermute_b32 v35, v36, v34
	v_bitop3_b32 v36, v42, 16, v211 bitop3:0x6c
	s_waitcnt lgkmcnt(0)
	v_add_f32_e32 v34, v34, v35
	ds_bpermute_b32 v36, v36, v34
	v_mov_b32_e32 v35, v33
	s_waitcnt lgkmcnt(0)
	v_add_f32_e32 v36, v34, v36
	ds_bpermute_b32 v37, v37, v36
	v_lshlrev_b32_e32 v34, 3, v117
	s_waitcnt lgkmcnt(0)
	v_add_f32_e32 v40, v36, v37
	ds_bpermute_b32 v39, v39, v40
	v_lshlrev_b64 v[36:37], 11, v[66:67]
	v_lshl_add_u64 v[36:37], s[30:31], 0, v[36:37]
	v_lshl_add_u64 v[60:61], v[36:37], 0, v[34:35]
	s_waitcnt lgkmcnt(0)
	v_add_f32_e32 v34, v40, v39
	v_fmamk_f32 v34, v34, 0x3a800000, v203
	v_rsq_f32_e32 v62, v34
	v_lshl_add_u64 v[34:35], v[26:27], 0, v[72:73]
	v_mov_b32_e32 v73, v202
	v_pk_mul_f32 v[12:13], v[12:13], v[62:63] op_sel_hi:[1,0]
	v_pk_mul_f32 v[14:15], v[14:15], v[62:63] op_sel_hi:[1,0]
	v_pk_mul_f32 v[12:13], v[20:21], v[12:13]
	v_pk_mul_f32 v[14:15], v[22:23], v[14:15]
	v_pk_fma_f32 v[64:65], v[16:17], v[12:13], v[28:29]
	v_pk_fma_f32 v[58:59], v[18:19], v[14:15], v[30:31]
	v_cvt_pk_bf16_f32 v12, v64, v65
	v_cvt_pk_bf16_f32 v13, v58, v59
	global_store_dwordx2 v[60:61], v[12:13], off
	global_load_dwordx4 v[28:31], v32, s[26:27] offset:1024
	s_nop 0
	global_load_dwordx4 v[34:37], v[34:35], off
	s_nop 0
	global_load_dwordx4 v[38:41], v[24:25], off offset:1024
	v_pk_mul_f32 v[44:45], v[8:9], v[62:63] op_sel_hi:[1,0]
	v_pk_mul_f32 v[46:47], v[10:11], v[62:63] op_sel_hi:[1,0]
	v_or_b32_e32 v12, 0x200, v63
	v_lshlrev_b32_e32 v74, 2, v12
	global_load_dwordx4 v[20:23], v32, s[12:13]
	global_load_dwordx4 v[8:11], v[82:83], off offset:-4096
	global_load_dwordx4 v[12:15], v[82:83], off
	global_load_dwordx4 v[16:19], v[84:85], off
	v_lshl_add_u64 v[42:43], v[26:27], 0, v[74:75]
	v_pk_mul_f32 v[4:5], v[4:5], v[62:63] op_sel_hi:[1,0]
	v_pk_mul_f32 v[6:7], v[6:7], v[62:63] op_sel_hi:[1,0]
	v_pk_mul_f32 v[0:1], v[0:1], v[62:63] op_sel_hi:[1,0]
	v_pk_mul_f32 v[2:3], v[2:3], v[62:63] op_sel_hi:[1,0]
	v_mov_b32_e32 v75, v202
	s_waitcnt vmcnt(6)
; DI unsigned pk2(float a, float b) { f2_t v = {a, b}; bf2_t r = __builtin_convertvector(v, bf2_t); return __builtin_bit_cast(unsigned, r); }
; template <int WHICH>
; DI void norm_item(const CP& p, int l, int item) {
;     ...
; #pragma unroll
;       for (int q = 0; q < 4; ++q) {
;         const int col = q * 256 + lane * 4;
;         fl4 g = *(const fl4*)(gain + col);
;         fl4 sh = *(const fl4*)(md + col);
;         fl4 sc = *(const fl4*)(md + 1024 + col);
;         fl4 h;
;         h.x = xv[q].x * rstd * g.x * (1.f + sc.x) + sh.x;
;         h.y = xv[q].y * rstd * g.y * (1.f + sc.y) + sh.y;
;         h.z = xv[q].z * rstd * g.z * (1.f + sc.z) + sh.z;
;         h.w = xv[q].w * rstd * g.w * (1.f + sc.w) + sh.w;
;         u32x2 v;
;         v.x = pk2(h.x, h.y); v.y = pk2(h.z, h.w);
;         *(u32x2*)(p.hbuf + (size_t)t * 1024 + col) = v;
;         if (WHICH == 1) {
;           const float* wf = p.wf + (size_t)l * 4096 + col;
;           fl4 w0 = *(const fl4*)(wf), w1 = *(const fl4*)(wf + 1024), w2 = *(const fl4*)(wf + 2048), w3 = *(const fl4*)(wf + 3072);
;           f0 += h.x * w0.x + h.y * w0.y + h.z * w0.z + h.w * w0.w;
;           f1 += h.x * w1.x + h.y * w1.y + h.z * w1.z + h.w * w1.w;
;           f2 += h.x * w2.x + h.y * w2.y + h.z * w2.z + h.w * w2.w;
;           f3 += h.x * w3.x + h.y * w3.y + h.z * w3.z + h.w * w3.w;
;         }
	v_pk_mul_f32 v[28:29], v[44:45], v[28:29]
	s_waitcnt vmcnt(5)
	v_pk_add_f32 v[34:35], v[34:35], 1.0 op_sel_hi:[1,0]
	v_pk_mul_f32 v[30:31], v[46:47], v[30:31]
	v_pk_add_f32 v[36:37], v[36:37], 1.0 op_sel_hi:[1,0]
	s_waitcnt vmcnt(4)
	v_pk_fma_f32 v[80:81], v[28:29], v[34:35], v[38:39]
	v_pk_fma_f32 v[78:79], v[30:31], v[36:37], v[40:41]
	v_cvt_pk_bf16_f32 v28, v80, v81
	v_cvt_pk_bf16_f32 v29, v78, v79
	global_store_dwordx2 v[60:61], v[28:29], off offset:512
	global_load_dwordx4 v[28:31], v32, s[26:27] offset:2048
	s_nop 0
	global_load_dwordx4 v[34:37], v[42:43], off
	global_load_dwordx4 v[94:97], v[24:25], off offset:2048
	v_or_b32_e32 v38, 0x300, v63
	v_lshlrev_b32_e32 v76, 2, v38
	v_lshl_add_u64 v[26:27], v[26:27], 0, v[76:77]
	global_load_dwordx4 v[38:41], v32, s[12:13] offset:1024
	global_load_dwordx4 v[42:45], v[82:83], off offset:1024
	global_load_dwordx4 v[50:53], v[90:91], off offset:1024
	global_load_dwordx4 v[46:49], v[84:85], off offset:1024
	s_waitcnt vmcnt(10)
	v_mul_f32_e32 v62, v9, v65
	s_waitcnt vmcnt(9)
	v_mul_f32_e32 v106, v13, v65
	v_fmac_f32_e32 v62, v8, v64
	v_fmac_f32_e32 v106, v12, v64
	s_waitcnt vmcnt(8)
	v_mul_f32_e32 v17, v17, v65
	v_fmac_f32_e32 v17, v16, v64
	v_fmac_f32_e32 v17, v18, v58
	v_mul_f32_e32 v21, v21, v65
	v_fmac_f32_e32 v106, v14, v58
	v_fmac_f32_e32 v17, v19, v59
	v_fmac_f32_e32 v21, v20, v64
	v_fmac_f32_e32 v106, v15, v59
	v_add_f32_e32 v15, 0, v17
	v_fmac_f32_e32 v21, v22, v58
	v_fmac_f32_e32 v62, v10, v58
	v_fmac_f32_e32 v21, v23, v59
	v_fmac_f32_e32 v62, v11, v59
	v_add_f32_e32 v10, 0, v21
	v_add_f32_e32 v11, 0, v62
	v_add_f32_e32 v14, 0, v106
	v_mov_b32_e32 v77, v202
	s_waitcnt vmcnt(6)
	v_pk_mul_f32 v[4:5], v[4:5], v[28:29]
	s_waitcnt vmcnt(5)
	v_pk_add_f32 v[28:29], v[34:35], 1.0 op_sel_hi:[1,0]
	v_pk_mul_f32 v[6:7], v[6:7], v[30:31]
	v_pk_add_f32 v[30:31], v[36:37], 1.0 op_sel_hi:[1,0]
	s_waitcnt vmcnt(4)
	v_pk_fma_f32 v[88:89], v[4:5], v[28:29], v[94:95]
	v_pk_fma_f32 v[86:87], v[6:7], v[30:31], v[96:97]
	v_cvt_pk_bf16_f32 v4, v88, v89
	v_cvt_pk_bf16_f32 v5, v86, v87
	global_store_dwordx2 v[60:61], v[4:5], off offset:1024
	global_load_dwordx4 v[94:97], v32, s[26:27] offset:3072
	global_load_dwordx4 v[98:101], v[26:27], off
	global_load_dwordx4 v[102:105], v[24:25], off offset:3072
	s_nop 0
	global_load_dwordx4 v[4:7], v32, s[12:13] offset:2048
	global_load_dwordx4 v[24:27], v[90:91], off offset:2048
	global_load_dwordx4 v[28:31], v[82:83], off offset:2048
	global_load_dwordx4 v[34:37], v[84:85], off offset:2048
	s_waitcnt vmcnt(11)
	v_mul_f32_e32 v16, v39, v81
	s_waitcnt vmcnt(9)
	v_mul_f32_e32 v17, v81, v51
	v_mul_f32_e32 v18, v81, v43
	v_fmac_f32_e32 v16, v38, v80
	v_fmac_f32_e32 v17, v80, v50
	v_fmac_f32_e32 v18, v80, v42
	v_fmac_f32_e32 v16, v40, v78
	v_fmac_f32_e32 v17, v78, v52
	v_fmac_f32_e32 v18, v78, v44
	s_waitcnt vmcnt(8)
	v_mul_f32_e32 v19, v81, v47
	v_fmac_f32_e32 v16, v41, v79
	v_fmac_f32_e32 v17, v79, v53
	v_fmac_f32_e32 v18, v79, v45
	v_fmac_f32_e32 v19, v80, v46
	v_add_f32_e32 v10, v10, v16
	v_add_f32_e32 v11, v11, v17
	v_add_f32_e32 v14, v14, v18
	v_fmac_f32_e32 v19, v78, v48
	v_fmac_f32_e32 v19, v79, v49
	v_add_f32_e32 v15, v15, v19
	s_waitcnt vmcnt(6)
	v_pk_mul_f32 v[0:1], v[0:1], v[94:95]
	s_waitcnt vmcnt(5)
	v_pk_add_f32 v[8:9], v[98:99], 1.0 op_sel_hi:[1,0]
	v_pk_mul_f32 v[2:3], v[2:3], v[96:97]
	v_pk_add_f32 v[12:13], v[100:101], 1.0 op_sel_hi:[1,0]
	s_waitcnt vmcnt(4)
	v_pk_fma_f32 v[8:9], v[0:1], v[8:9], v[102:103]
	v_pk_fma_f32 v[12:13], v[2:3], v[12:13], v[104:105]
	v_cvt_pk_bf16_f32 v0, v8, v9
	v_cvt_pk_bf16_f32 v1, v12, v13
	global_store_dwordx2 v[60:61], v[0:1], off offset:1536
	global_load_dwordx4 v[0:3], v32, s[12:13] offset:3072
	s_nop 0
	global_load_dwordx4 v[94:97], v[90:91], off offset:3072
	global_load_dwordx4 v[98:101], v[82:83], off offset:3072
	s_nop 0
	global_load_dwordx4 v[82:85], v[84:85], off offset:3072
	s_waitcnt vmcnt(8)
	v_mul_f32_e32 v5, v5, v89
	s_waitcnt vmcnt(7)
	v_mul_f32_e32 v16, v89, v25
	s_waitcnt vmcnt(6)
	v_mul_f32_e32 v17, v89, v29
	s_waitcnt vmcnt(5)
; template <int WHICH>
; DI void norm_item(const CP& p, int l, int item) {
;     ...
;         }
;       }
;       if (WHICH == 1) {
;         f0 = wave_sum(f0); f1 = wave_sum(f1); f2 = wave_sum(f2); f3 = wave_sum(f3);
;         if (lane < 4) {
;           float f = lane == 0 ? f0 : (lane == 1 ? f1 : (lane == 2 ? f2 : f3));
;           float v = f + p.fbias[l * 4 + lane];
;           float ls = fminf(v, 0.f) - log1pf(expf(-fabsf(v)));
;           const int s = t - b * S_;
;           p.lf[((size_t)b * 4 + lane) * S_ + s] = ls;
	v_mul_f32_e32 v18, v89, v35
	v_fmac_f32_e32 v5, v4, v88
	v_fmac_f32_e32 v16, v88, v24
	v_fmac_f32_e32 v17, v88, v28
	v_fmac_f32_e32 v18, v88, v34
	v_fmac_f32_e32 v5, v6, v86
	v_fmac_f32_e32 v16, v86, v26
	v_fmac_f32_e32 v17, v86, v30
	v_fmac_f32_e32 v18, v86, v36
	v_fmac_f32_e32 v5, v7, v87
	v_fmac_f32_e32 v16, v87, v27
	v_fmac_f32_e32 v17, v87, v31
	v_fmac_f32_e32 v18, v87, v37
	v_add_f32_e32 v4, v10, v5
	v_add_f32_e32 v5, v11, v16
	v_add_f32_e32 v6, v14, v17
	v_add_f32_e32 v7, v15, v18
	s_load_dwordx2 s[6:7], s[0:1], 0x48
	v_lshlrev_b32_e32 v10, 2, v73
	v_lshlrev_b32_e32 v11, 2, v75
	v_lshlrev_b32_e32 v14, 2, v77
	v_lshlrev_b32_e32 v15, 2, v93
	v_bitop3_b32 v16, v10, s84, v211 bitop3:0x6c
	v_bitop3_b32 v21, v11, s84, v211 bitop3:0x6c
	v_bitop3_b32 v26, v14, s84, v211 bitop3:0x6c
	v_bitop3_b32 v31, v15, s84, v211 bitop3:0x6c
	v_bitop3_b32 v17, v10, 64, v211 bitop3:0x6c
	v_bitop3_b32 v22, v11, 64, v211 bitop3:0x6c
	v_bitop3_b32 v27, v14, 64, v211 bitop3:0x6c
	v_bitop3_b32 v18, v10, 32, v211 bitop3:0x6c
	v_bitop3_b32 v23, v11, 32, v211 bitop3:0x6c
	v_bitop3_b32 v28, v14, 32, v211 bitop3:0x6c
	v_bitop3_b32 v19, v10, 16, v211 bitop3:0x6c
	v_bitop3_b32 v24, v11, 16, v211 bitop3:0x6c
	v_bitop3_b32 v29, v14, 16, v211 bitop3:0x6c
	v_bitop3_b32 v20, v10, 8, v211 bitop3:0x6c
	v_bitop3_b32 v25, v11, 8, v211 bitop3:0x6c
	v_bitop3_b32 v30, v14, 8, v211 bitop3:0x6c
	v_bitop3_b32 v10, v10, 4, v211 bitop3:0x6c
	v_bitop3_b32 v11, v11, 4, v211 bitop3:0x6c
	v_bitop3_b32 v14, v14, 4, v211 bitop3:0x6c
	s_waitcnt lgkmcnt(0)
	v_lshl_add_u64 v[80:81], v[56:57], 2, s[6:7]
	s_load_dwordx2 s[6:7], s[0:1], 0x110
	s_waitcnt vmcnt(3)
	v_mul_f32_e32 v1, v1, v9
	s_waitcnt vmcnt(2)
	v_mul_f32_e32 v34, v9, v95
	s_waitcnt vmcnt(1)
	v_mul_f32_e32 v35, v9, v99
	s_waitcnt vmcnt(0)
	v_mul_f32_e32 v9, v9, v83
	v_fmac_f32_e32 v1, v0, v8
	v_fmac_f32_e32 v34, v8, v94
	v_fmac_f32_e32 v35, v8, v98
	v_fmac_f32_e32 v9, v8, v82
	v_fmac_f32_e32 v1, v2, v12
	v_fmac_f32_e32 v34, v12, v96
	v_fmac_f32_e32 v35, v12, v100
	v_fmac_f32_e32 v9, v12, v84
	v_fmac_f32_e32 v1, v3, v13
	v_fmac_f32_e32 v34, v13, v97
	v_fmac_f32_e32 v35, v13, v101
	v_fmac_f32_e32 v9, v13, v85
	v_add_f32_e32 v0, v4, v1
	v_add_f32_e32 v1, v5, v34
	v_add_f32_e32 v2, v6, v35
	v_add_f32_e32 v3, v7, v9
	ds_bpermute_b32 v4, v16, v0
	ds_bpermute_b32 v5, v21, v1
	ds_bpermute_b32 v6, v26, v2
	ds_bpermute_b32 v7, v31, v3
	v_bitop3_b32 v8, v15, 64, v211 bitop3:0x6c
	s_waitcnt lgkmcnt(0)
	v_add_f32_e32 v0, v0, v4
	v_add_f32_e32 v1, v1, v5
	v_add_f32_e32 v2, v2, v6
	v_add_f32_e32 v3, v3, v7
	ds_bpermute_b32 v4, v17, v0
	ds_bpermute_b32 v5, v22, v1
	ds_bpermute_b32 v6, v27, v2
	ds_bpermute_b32 v7, v8, v3
	v_bitop3_b32 v8, v15, 32, v211 bitop3:0x6c
	s_waitcnt lgkmcnt(3)
	v_add_f32_e32 v0, v0, v4
	s_waitcnt lgkmcnt(2)
	v_add_f32_e32 v1, v1, v5
	s_waitcnt lgkmcnt(1)
	v_add_f32_e32 v2, v2, v6
	s_waitcnt lgkmcnt(0)
	v_add_f32_e32 v3, v3, v7
	ds_bpermute_b32 v4, v18, v0
	ds_bpermute_b32 v5, v23, v1
	ds_bpermute_b32 v6, v28, v2
	ds_bpermute_b32 v7, v8, v3
	v_bitop3_b32 v8, v15, 16, v211 bitop3:0x6c
	s_waitcnt lgkmcnt(3)
	v_add_f32_e32 v0, v0, v4
	s_waitcnt lgkmcnt(2)
	v_add_f32_e32 v1, v1, v5
	s_waitcnt lgkmcnt(1)
	v_add_f32_e32 v2, v2, v6
	s_waitcnt lgkmcnt(0)
	v_add_f32_e32 v3, v3, v7
	ds_bpermute_b32 v4, v19, v0
	ds_bpermute_b32 v5, v24, v1
	ds_bpermute_b32 v6, v29, v2
	ds_bpermute_b32 v7, v8, v3
	v_bitop3_b32 v8, v15, 8, v211 bitop3:0x6c
	s_waitcnt lgkmcnt(3)
	v_add_f32_e32 v0, v0, v4
	s_waitcnt lgkmcnt(2)
	v_add_f32_e32 v1, v1, v5
	s_waitcnt lgkmcnt(1)
	v_add_f32_e32 v2, v2, v6
	s_waitcnt lgkmcnt(0)
	v_add_f32_e32 v3, v3, v7
	ds_bpermute_b32 v4, v20, v0
	ds_bpermute_b32 v5, v25, v1
	ds_bpermute_b32 v7, v30, v2
	ds_bpermute_b32 v8, v8, v3
	v_bitop3_b32 v9, v15, 4, v211 bitop3:0x6c
	s_waitcnt lgkmcnt(3)
	v_add_f32_e32 v6, v0, v4
	s_waitcnt lgkmcnt(2)
	v_add_f32_e32 v0, v1, v5
	s_waitcnt lgkmcnt(1)
	v_add_f32_e32 v2, v2, v7
	s_waitcnt lgkmcnt(0)
	v_add_f32_e32 v3, v3, v8
	ds_bpermute_b32 v7, v10, v6
	ds_bpermute_b32 v1, v11, v0
	ds_bpermute_b32 v4, v14, v2
	ds_bpermute_b32 v5, v9, v3
	v_lshlrev_b32_e32 v8, 16, v117
	v_mov_b32_e32 v9, v33
	v_lshl_add_u64 v[78:79], s[6:7], 0, v[8:9]
	s_and_saveexec_b64 s[64:65], s[4:5]
	s_cbranch_execz .LBB0_639
	s_waitcnt lgkmcnt(3)
	v_add_f32_e32 v6, v6, v7
	v_cmp_lt_i32_e64 s[6:7], 0, v117
	s_and_saveexec_b64 s[66:67], s[6:7]
	s_cbranch_execz .LBB0_638
	v_cmp_ne_u32_e64 s[6:7], 1, v117
	s_and_saveexec_b64 s[38:39], s[6:7]
	s_xor_b64 s[6:7], exec, s[38:39]
	s_cbranch_execz .LBB0_635
	s_waitcnt lgkmcnt(1)
	v_add_f32_e32 v0, v2, v4
	s_waitcnt lgkmcnt(0)
	v_add_f32_e32 v1, v3, v5
	v_cndmask_b32_e32 v6, v1, v0, vcc

; DI unsigned pk2(float a, float b) { f2_t v = {a, b}; bf2_t r = __builtin_convertvector(v, bf2_t); return __builtin_bit_cast(unsigned, r); }
; template <int WHICH>
; DI void norm_item(const CP& p, int l, int item) {
;     ...
;   for (int it = 0; it < 4; ++it) {
;     const int t = item * 32 + w * 4 + it;
;     const int b = t / S_;
;     fl4 xv[4];
;     float ssq = 0.f;
; #pragma unroll
;     for (int q = 0; q < 4; ++q) {
;       xv[q] = *(const fl4*)(xs + (size_t)t * 1024 + q * 256 + lane * 4);
;       ssq += xv[q].x * xv[q].x + xv[q].y * xv[q].y + xv[q].z * xv[q].z + xv[q].w * xv[q].w;
;     }
;     ssq = wave_sum(ssq);
;     const float rstd = __builtin_amdgcn_rsqf(ssq * (1.f / 1024.f) + 1e-6f);
;     if (WHICH == 3) {
; #pragma unroll
;       for (int q = 0; q < 4; ++q) {
;         fl4 g = *(const fl4*)(gain + q * 256 + lane * 4);
;         fl4 o;
;         o.x = xv[q].x * rstd * g.x; o.y = xv[q].y * rstd * g.y; o.z = xv[q].z * rstd * g.z; o.w = xv[q].w * rstd * g.w;
;         *(fl4*)(p.out + (size_t)t * 1024 + q * 256 + lane * 4) = o;
;       }
;     } else {
;       const float* md = p.mod + ((size_t)l * 2 + b) * 6144 + (WHICH == 1 ? 0 : 3072);
;       float f0 = 0.f, f1 = 0.f, f2 = 0.f, f3 = 0.f;
; #pragma unroll
;       for (int q = 0; q < 4; ++q) {
;         const int col = q * 256 + lane * 4;
;         fl4 g = *(const fl4*)(gain + col);
;         fl4 sh = *(const fl4*)(md + col);
;         fl4 sc = *(const fl4*)(md + 1024 + col);
;         fl4 h;
;         h.x = xv[q].x * rstd * g.x * (1.f + sc.x) + sh.x;
;         h.y = xv[q].y * rstd * g.y * (1.f + sc.y) + sh.y;
;         h.z = xv[q].z * rstd * g.z * (1.f + sc.z) + sh.z;
;         h.w = xv[q].w * rstd * g.w * (1.f + sc.w) + sh.w;
;         u32x2 v;
;         v.x = pk2(h.x, h.y); v.y = pk2(h.z, h.w);
;         *(u32x2*)(p.hbuf + (size_t)t * 1024 + col) = v;
;         if (WHICH == 1) {
;           const float* wf = p.wf + (size_t)l * 4096 + col;
;           fl4 w0 = *(const fl4*)(wf), w1 = *(const fl4*)(wf + 1024), w2 = *(const fl4*)(wf + 2048), w3 = *(const fl4*)(wf + 3072);
;           f0 += h.x * w0.x + h.y * w0.y + h.z * w0.z + h.w * w0.w;
;           f1 += h.x * w1.x + h.y * w1.y + h.z * w1.z + h.w * w1.w;
;           f2 += h.x * w2.x + h.y * w2.y + h.z * w2.z + h.w * w2.w;
;           f3 += h.x * w3.x + h.y * w3.y + h.z * w3.z + h.w * w3.w;
;         }
.LBB0_639:
	s_or_b64 exec, exec, s[64:65]
	v_add_u32_e32 v16, 1, v66
	v_ashrrev_i32_e32 v17, 31, v16
	s_waitcnt lgkmcnt(2)
	v_lshlrev_b64 v[0:1], 12, v[16:17]
	v_lshl_add_u64 v[0:1], v[70:71], 0, v[0:1]
	v_mov_b64_e32 v[12:13], v[168:169]
	v_mov_b64_e32 v[14:15], v[170:171]
	v_mov_b64_e32 v[8:9], v[172:173]
	v_mov_b64_e32 v[10:11], v[174:175]
	s_waitcnt lgkmcnt(0)
	v_mov_b64_e32 v[4:5], v[176:177]
	v_mov_b64_e32 v[6:7], v[178:179]
	s_nop 0
	v_mov_b64_e32 v[0:1], v[180:181]
	v_mov_b64_e32 v[2:3], v[182:183]
	s_mov_b64 s[6:7], 0x2000
	v_lshl_add_u64 v[104:105], v[68:69], 0, s[6:7]
	s_mov_b64 s[6:7], 0x1400
	v_lshl_add_u64 v[96:97], v[68:69], 0, s[6:7]
	s_mov_b64 s[6:7], 0x2400
	v_lshl_add_u64 v[98:99], v[68:69], 0, s[6:7]
	s_mov_b64 s[6:7], 0x3400
	v_lshl_add_u64 v[100:101], v[68:69], 0, s[6:7]
	s_mov_b64 s[6:7], 0x1800
	v_lshl_add_u64 v[88:89], v[68:69], 0, s[6:7]
	s_mov_b64 s[6:7], 0x2800
	v_lshrrev_b32_e32 v20, 18, v17
	v_lshl_add_u64 v[90:91], v[68:69], 0, s[6:7]
	s_mov_b64 s[6:7], 0x3800
	v_add_u32_e32 v20, v16, v20
	v_lshl_add_u64 v[92:93], v[68:69], 0, s[6:7]
	s_mov_b64 s[6:7], 0x1c00
	v_ashrrev_i32_e32 v110, 14, v20
	v_lshl_add_u64 v[82:83], v[68:69], 0, s[6:7]
	s_mov_b64 s[6:7], 0x2c00
	v_ashrrev_i32_e32 v111, 31, v110
	v_lshl_add_u64 v[84:85], v[68:69], 0, s[6:7]
	s_mov_b64 s[6:7], 0x3c00
	v_mov_b64_e32 v[18:19], s[14:15]
	v_lshl_add_u64 v[20:21], s[28:29], 0, v[110:111]
	v_lshl_add_u64 v[86:87], v[68:69], 0, s[6:7]
	v_mad_u64_u32 v[22:23], s[6:7], v20, s93, v[18:19]
	v_mad_i32_i24 v23, v21, s93, v23
	v_lshl_add_u64 v[94:95], s[26:27], 0, v[32:33]
	v_lshlrev_b32_e32 v32, 2, v63
	v_lshl_add_u64 v[24:25], v[22:23], 0, s[60:61]
	v_mov_b32_e32 v38, v202
	v_lshl_add_u64 v[18:19], v[24:25], 0, v[32:33]
	global_load_dwordx4 v[18:21], v[18:19], off
	s_nop 0
	global_load_dwordx4 v[28:31], v[94:95], off
	v_lshl_add_u64 v[26:27], v[22:23], 0, v[32:33]
	global_load_dwordx4 v[34:37], v[26:27], off
	v_lshlrev_b32_e32 v44, 2, v38
	v_bitop3_b32 v45, v44, s84, v211 bitop3:0x6c
	v_lshlrev_b64 v[16:17], 11, v[16:17]
	v_lshlrev_b32_e32 v108, 1, v63
	v_mov_b32_e32 v109, v33
	v_lshl_add_u64 v[16:17], s[30:31], 0, v[16:17]
	v_lshl_add_u64 v[112:113], v[16:17], 0, v[108:109]
	v_mov_b32_e32 v73, v33
	v_lshl_add_u64 v[102:103], v[68:69], 0, s[60:61]
	v_lshl_add_u64 v[106:107], v[68:69], 0, s[54:55]
	v_mov_b32_e32 v75, v33
	v_mov_b32_e32 v77, v33
	v_mov_b32_e32 v109, v202
	s_waitcnt vmcnt(6)
	v_mul_f32_e32 v46, v13, v13
	s_waitcnt vmcnt(5)
	v_mul_f32_e32 v47, v9, v9
	s_waitcnt vmcnt(4)
	v_mov_b32_e32 v38, v5
	s_waitcnt vmcnt(3)
	v_mov_b32_e32 v39, v1
	v_mov_b32_e32 v22, v4
	v_mov_b32_e32 v23, v0
	v_fmac_f32_e32 v46, v12, v12
	v_fmac_f32_e32 v47, v8, v8
	v_pk_mul_f32 v[38:39], v[38:39], v[38:39]
	v_mov_b32_e32 v40, v6
	v_mov_b32_e32 v41, v2
	v_fmac_f32_e32 v46, v14, v14
	v_fmac_f32_e32 v47, v10, v10
	v_pk_fma_f32 v[22:23], v[22:23], v[22:23], v[38:39]
	v_mov_b32_e32 v42, v7
	v_mov_b32_e32 v43, v3
	v_fmac_f32_e32 v46, v15, v15
	v_fmac_f32_e32 v47, v11, v11
	v_pk_fma_f32 v[22:23], v[40:41], v[40:41], v[22:23]
	v_add_f32_e32 v38, v46, v47
	v_pk_fma_f32 v[22:23], v[42:43], v[42:43], v[22:23]
	v_lshl_add_u64 v[42:43], v[24:25], 0, v[74:75]
	v_add_f32_e32 v22, v38, v22
	v_add_f32_e32 v22, v22, v23
	ds_bpermute_b32 v23, v45, v22
	v_bitop3_b32 v38, v44, 64, v211 bitop3:0x6c
	v_mov_b32_e32 v75, v202
	s_waitcnt lgkmcnt(0)
	v_add_f32_e32 v22, v22, v23
	ds_bpermute_b32 v23, v38, v22
	v_bitop3_b32 v38, v44, 32, v211 bitop3:0x6c
	s_waitcnt lgkmcnt(0)
	v_add_f32_e32 v22, v22, v23
	ds_bpermute_b32 v23, v38, v22
	v_bitop3_b32 v38, v44, 16, v211 bitop3:0x6c
	s_waitcnt vmcnt(2)
	v_pk_add_f32 v[18:19], v[18:19], 1.0 op_sel_hi:[1,0]
	v_pk_add_f32 v[20:21], v[20:21], 1.0 op_sel_hi:[1,0]
	s_waitcnt lgkmcnt(0)
	v_add_f32_e32 v22, v22, v23
	ds_bpermute_b32 v23, v38, v22
	v_bitop3_b32 v38, v44, 8, v211 bitop3:0x6c
	s_waitcnt lgkmcnt(0)
	v_add_f32_e32 v22, v22, v23
	ds_bpermute_b32 v23, v38, v22
	v_bitop3_b32 v38, v44, 4, v211 bitop3:0x6c
	s_waitcnt lgkmcnt(0)
	v_add_f32_e32 v22, v22, v23
	ds_bpermute_b32 v23, v38, v22
	s_waitcnt lgkmcnt(0)
	v_add_f32_e32 v16, v22, v23
	v_fmamk_f32 v16, v16, 0x3a800000, v203
	v_rsq_f32_e32 v116, v16
	v_lshl_add_u64 v[16:17], v[24:25], 0, v[72:73]
	v_lshl_add_u64 v[24:25], v[24:25], 0, v[76:77]
	v_mov_b32_e32 v73, v202
	v_pk_mul_f32 v[12:13], v[12:13], v[116:117] op_sel_hi:[1,0]
	v_pk_mul_f32 v[14:15], v[14:15], v[116:117] op_sel_hi:[1,0]
	s_waitcnt vmcnt(1)
	v_pk_mul_f32 v[12:13], v[28:29], v[12:13]
	v_pk_mul_f32 v[14:15], v[30:31], v[14:15]
	s_waitcnt vmcnt(0)
	v_pk_fma_f32 v[118:119], v[18:19], v[12:13], v[34:35]
	v_pk_fma_f32 v[114:115], v[20:21], v[14:15], v[36:37]
	v_cvt_pk_bf16_f32 v12, v118, v119
	v_cvt_pk_bf16_f32 v13, v114, v115
	global_store_dwordx2 v[112:113], v[12:13], off
	global_load_dwordx4 v[28:31], v[94:95], off offset:1024
	global_load_dwordx4 v[34:37], v[16:17], off
	global_load_dwordx4 v[38:41], v[26:27], off offset:1024
	v_pk_mul_f32 v[44:45], v[8:9], v[116:117] op_sel_hi:[1,0]
	v_pk_mul_f32 v[46:47], v[10:11], v[116:117] op_sel_hi:[1,0]
	global_load_dwordx4 v[8:11], v[68:69], off
	global_load_dwordx4 v[12:15], v[102:103], off
	global_load_dwordx4 v[16:19], v[104:105], off
	global_load_dwordx4 v[20:23], v[106:107], off
	v_pk_mul_f32 v[4:5], v[4:5], v[116:117] op_sel_hi:[1,0]
	v_pk_mul_f32 v[6:7], v[6:7], v[116:117] op_sel_hi:[1,0]
	v_pk_mul_f32 v[0:1], v[0:1], v[116:117] op_sel_hi:[1,0]
	v_pk_mul_f32 v[2:3], v[2:3], v[116:117] op_sel_hi:[1,0]
	v_mov_b32_e32 v77, v202
	s_waitcnt vmcnt(6)
	v_pk_mul_f32 v[28:29], v[44:45], v[28:29]
	s_waitcnt vmcnt(5)
; DI unsigned pk2(float a, float b) { f2_t v = {a, b}; bf2_t r = __builtin_convertvector(v, bf2_t); return __builtin_bit_cast(unsigned, r); }
; template <int WHICH>
; DI void norm_item(const CP& p, int l, int item) {
;     ...
; #pragma unroll
;       for (int q = 0; q < 4; ++q) {
;         const int col = q * 256 + lane * 4;
;         fl4 g = *(const fl4*)(gain + col);
;         fl4 sh = *(const fl4*)(md + col);
;         fl4 sc = *(const fl4*)(md + 1024 + col);
;         fl4 h;
;         h.x = xv[q].x * rstd * g.x * (1.f + sc.x) + sh.x;
;         h.y = xv[q].y * rstd * g.y * (1.f + sc.y) + sh.y;
;         h.z = xv[q].z * rstd * g.z * (1.f + sc.z) + sh.z;
;         h.w = xv[q].w * rstd * g.w * (1.f + sc.w) + sh.w;
;         u32x2 v;
;         v.x = pk2(h.x, h.y); v.y = pk2(h.z, h.w);
;         *(u32x2*)(p.hbuf + (size_t)t * 1024 + col) = v;
;         if (WHICH == 1) {
;           const float* wf = p.wf + (size_t)l * 4096 + col;
;           fl4 w0 = *(const fl4*)(wf), w1 = *(const fl4*)(wf + 1024), w2 = *(const fl4*)(wf + 2048), w3 = *(const fl4*)(wf + 3072);
;           f0 += h.x * w0.x + h.y * w0.y + h.z * w0.z + h.w * w0.w;
;           f1 += h.x * w1.x + h.y * w1.y + h.z * w1.z + h.w * w1.w;
;           f2 += h.x * w2.x + h.y * w2.y + h.z * w2.z + h.w * w2.w;
;           f3 += h.x * w3.x + h.y * w3.y + h.z * w3.z + h.w * w3.w;
;         }
	v_pk_add_f32 v[34:35], v[34:35], 1.0 op_sel_hi:[1,0]
	v_pk_mul_f32 v[30:31], v[46:47], v[30:31]
	v_pk_add_f32 v[36:37], v[36:37], 1.0 op_sel_hi:[1,0]
	s_waitcnt vmcnt(4)
	v_pk_fma_f32 v[122:123], v[28:29], v[34:35], v[38:39]
	v_pk_fma_f32 v[120:121], v[30:31], v[36:37], v[40:41]
	v_cvt_pk_bf16_f32 v28, v122, v123
	v_cvt_pk_bf16_f32 v29, v120, v121
	global_store_dwordx2 v[112:113], v[28:29], off offset:512
	global_load_dwordx4 v[28:31], v[94:95], off offset:2048
	s_nop 0
	global_load_dwordx4 v[34:37], v[42:43], off
	global_load_dwordx4 v[54:57], v[26:27], off offset:2048
	global_load_dwordx4 v[38:41], v[68:69], off offset:1024
	s_nop 0
	global_load_dwordx4 v[42:45], v[96:97], off
	global_load_dwordx4 v[46:49], v[98:99], off
	global_load_dwordx4 v[50:53], v[100:101], off
	s_waitcnt vmcnt(11)
	v_mul_f32_e32 v116, v9, v119
	s_waitcnt vmcnt(10)
	v_mul_f32_e32 v128, v13, v119
	v_fmac_f32_e32 v116, v8, v118
	v_fmac_f32_e32 v128, v12, v118
	s_waitcnt vmcnt(9)
	v_mul_f32_e32 v17, v17, v119
	v_fmac_f32_e32 v17, v16, v118
	v_fmac_f32_e32 v17, v18, v114
	v_fmac_f32_e32 v17, v19, v115
	v_fmac_f32_e32 v128, v14, v114
	v_add_f32_e32 v14, 0, v17
	v_fmac_f32_e32 v116, v10, v114
	s_waitcnt vmcnt(8)
	v_mul_f32_e32 v21, v21, v119
	v_fmac_f32_e32 v116, v11, v115
	v_fmac_f32_e32 v128, v15, v115
	v_fmac_f32_e32 v21, v20, v118
	v_add_f32_e32 v10, 0, v116
	v_add_f32_e32 v11, 0, v128
	v_fmac_f32_e32 v21, v22, v114
	v_fmac_f32_e32 v21, v23, v115
	v_add_f32_e32 v15, 0, v21
	s_waitcnt vmcnt(3)
	v_mul_f32_e32 v16, v39, v123
	v_pk_mul_f32 v[4:5], v[4:5], v[28:29]
	v_pk_add_f32 v[28:29], v[34:35], 1.0 op_sel_hi:[1,0]
	v_pk_mul_f32 v[6:7], v[6:7], v[30:31]
	v_pk_add_f32 v[30:31], v[36:37], 1.0 op_sel_hi:[1,0]
	v_pk_fma_f32 v[126:127], v[4:5], v[28:29], v[54:55]
	v_pk_fma_f32 v[124:125], v[6:7], v[30:31], v[56:57]
	v_cvt_pk_bf16_f32 v4, v126, v127
	v_cvt_pk_bf16_f32 v5, v124, v125
	global_store_dwordx2 v[112:113], v[4:5], off offset:1024
	global_load_dwordx4 v[58:61], v[94:95], off offset:3072
	global_load_dwordx4 v[62:65], v[24:25], off
	global_load_dwordx4 v[54:57], v[26:27], off offset:3072
	s_nop 0
	global_load_dwordx4 v[4:7], v[68:69], off offset:2048
	global_load_dwordx4 v[24:27], v[88:89], off
	global_load_dwordx4 v[28:31], v[90:91], off
	global_load_dwordx4 v[34:37], v[92:93], off
	s_waitcnt vmcnt(10)
	v_mul_f32_e32 v17, v123, v43
	s_waitcnt vmcnt(9)
	v_mul_f32_e32 v18, v123, v47
	v_fmac_f32_e32 v16, v38, v122
	v_fmac_f32_e32 v17, v122, v42
	v_fmac_f32_e32 v18, v122, v46
	v_fmac_f32_e32 v16, v40, v120
	v_fmac_f32_e32 v17, v120, v44
	v_fmac_f32_e32 v18, v120, v48
	s_waitcnt vmcnt(8)
	v_mul_f32_e32 v19, v123, v51
	v_fmac_f32_e32 v16, v41, v121
	v_fmac_f32_e32 v17, v121, v45
	v_fmac_f32_e32 v18, v121, v49
	v_fmac_f32_e32 v19, v122, v50
	v_add_f32_e32 v10, v10, v16
	v_add_f32_e32 v11, v11, v17
	v_add_f32_e32 v14, v14, v18
	v_fmac_f32_e32 v19, v120, v52
	v_fmac_f32_e32 v19, v121, v53
	v_add_f32_e32 v15, v15, v19
	s_waitcnt vmcnt(6)
	v_pk_mul_f32 v[0:1], v[0:1], v[58:59]
	s_waitcnt vmcnt(5)
	v_pk_add_f32 v[8:9], v[62:63], 1.0 op_sel_hi:[1,0]
	v_pk_mul_f32 v[2:3], v[2:3], v[60:61]
	v_pk_add_f32 v[12:13], v[64:65], 1.0 op_sel_hi:[1,0]
	s_waitcnt vmcnt(4)
	v_pk_fma_f32 v[8:9], v[0:1], v[8:9], v[54:55]
	v_pk_fma_f32 v[12:13], v[2:3], v[12:13], v[56:57]
	v_cvt_pk_bf16_f32 v0, v8, v9
	v_cvt_pk_bf16_f32 v1, v12, v13
	global_store_dwordx2 v[112:113], v[0:1], off offset:1536
	global_load_dwordx4 v[0:3], v[68:69], off offset:3072
	s_nop 0
	global_load_dwordx4 v[54:57], v[82:83], off
	global_load_dwordx4 v[58:61], v[84:85], off
	global_load_dwordx4 v[62:65], v[86:87], off
	s_waitcnt vmcnt(8)
	v_mul_f32_e32 v5, v5, v127
	s_waitcnt vmcnt(7)
	v_mul_f32_e32 v16, v127, v25
	s_waitcnt vmcnt(6)
	v_mul_f32_e32 v17, v127, v29
	s_waitcnt vmcnt(5)
	v_mul_f32_e32 v18, v127, v35
	v_fmac_f32_e32 v5, v4, v126
	v_fmac_f32_e32 v16, v126, v24
	v_fmac_f32_e32 v17, v126, v28
	v_fmac_f32_e32 v18, v126, v34
	v_fmac_f32_e32 v5, v6, v124
	v_fmac_f32_e32 v16, v124, v26
	v_fmac_f32_e32 v17, v124, v30
	v_fmac_f32_e32 v18, v124, v36
	v_fmac_f32_e32 v5, v7, v125
	v_fmac_f32_e32 v16, v125, v27
	v_fmac_f32_e32 v17, v125, v31
	v_fmac_f32_e32 v18, v125, v37
	v_add_f32_e32 v4, v10, v5
	v_add_f32_e32 v5, v11, v16
	v_add_f32_e32 v6, v14, v17
	v_add_f32_e32 v7, v15, v18
	s_waitcnt vmcnt(3)
; template <int WHICH>
; DI void norm_item(const CP& p, int l, int item) {
;     ...
;         }
;       }
;       if (WHICH == 1) {
;         f0 = wave_sum(f0); f1 = wave_sum(f1); f2 = wave_sum(f2); f3 = wave_sum(f3);
;         if (lane < 4) {
;           float f = lane == 0 ? f0 : (lane == 1 ? f1 : (lane == 2 ? f2 : f3));
;           float v = f + p.fbias[l * 4 + lane];
;           float ls = fminf(v, 0.f) - log1pf(expf(-fabsf(v)));
;           const int s = t - b * S_;
;           p.lf[((size_t)b * 4 + lane) * S_ + s] = ls;
	v_mul_f32_e32 v1, v1, v9
	s_waitcnt vmcnt(2)
	v_mul_f32_e32 v34, v9, v55
	s_waitcnt vmcnt(1)
	v_mul_f32_e32 v35, v9, v59
	s_waitcnt vmcnt(0)
	v_mul_f32_e32 v9, v9, v63
	v_fmac_f32_e32 v1, v0, v8
	v_fmac_f32_e32 v34, v8, v54
	v_fmac_f32_e32 v35, v8, v58
	v_fmac_f32_e32 v9, v8, v62
	v_fmac_f32_e32 v1, v2, v12
	v_fmac_f32_e32 v34, v12, v56
	v_fmac_f32_e32 v35, v12, v60
	v_fmac_f32_e32 v9, v12, v64
	v_lshlrev_b32_e32 v10, 2, v73
	v_lshlrev_b32_e32 v11, 2, v75
	v_lshlrev_b32_e32 v14, 2, v77
	v_lshlrev_b32_e32 v15, 2, v109
	v_fmac_f32_e32 v1, v3, v13
	v_fmac_f32_e32 v34, v13, v57
	v_fmac_f32_e32 v35, v13, v61
	v_fmac_f32_e32 v9, v13, v65
	v_bitop3_b32 v16, v10, s84, v211 bitop3:0x6c
	v_bitop3_b32 v21, v11, s84, v211 bitop3:0x6c
	v_bitop3_b32 v26, v14, s84, v211 bitop3:0x6c
	v_bitop3_b32 v31, v15, s84, v211 bitop3:0x6c
	v_add_f32_e32 v0, v4, v1
	v_add_f32_e32 v1, v5, v34
	v_add_f32_e32 v2, v6, v35
	v_add_f32_e32 v3, v7, v9
	ds_bpermute_b32 v4, v16, v0
	ds_bpermute_b32 v5, v21, v1
	ds_bpermute_b32 v6, v26, v2
	ds_bpermute_b32 v7, v31, v3
	v_bitop3_b32 v17, v10, 64, v211 bitop3:0x6c
	v_bitop3_b32 v22, v11, 64, v211 bitop3:0x6c
	v_bitop3_b32 v27, v14, 64, v211 bitop3:0x6c
	v_bitop3_b32 v8, v15, 64, v211 bitop3:0x6c
	s_waitcnt lgkmcnt(3)
	v_add_f32_e32 v0, v0, v4
	s_waitcnt lgkmcnt(2)
	v_add_f32_e32 v1, v1, v5
	s_waitcnt lgkmcnt(1)
	v_add_f32_e32 v2, v2, v6
	s_waitcnt lgkmcnt(0)
	v_add_f32_e32 v3, v3, v7
	ds_bpermute_b32 v4, v17, v0
	ds_bpermute_b32 v5, v22, v1
	ds_bpermute_b32 v6, v27, v2
	ds_bpermute_b32 v7, v8, v3
	v_bitop3_b32 v18, v10, 32, v211 bitop3:0x6c
	v_bitop3_b32 v23, v11, 32, v211 bitop3:0x6c
	v_bitop3_b32 v28, v14, 32, v211 bitop3:0x6c
	v_bitop3_b32 v8, v15, 32, v211 bitop3:0x6c
	s_waitcnt lgkmcnt(3)
	v_add_f32_e32 v0, v0, v4
	s_waitcnt lgkmcnt(2)
	v_add_f32_e32 v1, v1, v5
	s_waitcnt lgkmcnt(1)
	v_add_f32_e32 v2, v2, v6
	s_waitcnt lgkmcnt(0)
	v_add_f32_e32 v3, v3, v7
	ds_bpermute_b32 v4, v18, v0
	ds_bpermute_b32 v5, v23, v1
	ds_bpermute_b32 v6, v28, v2
	ds_bpermute_b32 v7, v8, v3
	v_bitop3_b32 v19, v10, 16, v211 bitop3:0x6c
	v_bitop3_b32 v24, v11, 16, v211 bitop3:0x6c
	v_bitop3_b32 v29, v14, 16, v211 bitop3:0x6c
	v_bitop3_b32 v8, v15, 16, v211 bitop3:0x6c
	s_waitcnt lgkmcnt(3)
	v_add_f32_e32 v0, v0, v4
	s_waitcnt lgkmcnt(2)
	v_add_f32_e32 v1, v1, v5
	s_waitcnt lgkmcnt(1)
	v_add_f32_e32 v2, v2, v6
	s_waitcnt lgkmcnt(0)
	v_add_f32_e32 v3, v3, v7
	ds_bpermute_b32 v4, v19, v0
	ds_bpermute_b32 v5, v24, v1
	ds_bpermute_b32 v6, v29, v2
	ds_bpermute_b32 v7, v8, v3
	v_bitop3_b32 v20, v10, 8, v211 bitop3:0x6c
	v_bitop3_b32 v25, v11, 8, v211 bitop3:0x6c
	v_bitop3_b32 v30, v14, 8, v211 bitop3:0x6c
	v_bitop3_b32 v8, v15, 8, v211 bitop3:0x6c
	s_waitcnt lgkmcnt(3)
	v_add_f32_e32 v0, v0, v4
	s_waitcnt lgkmcnt(2)
	v_add_f32_e32 v1, v1, v5
	s_waitcnt lgkmcnt(1)
	v_add_f32_e32 v4, v2, v6
	s_waitcnt lgkmcnt(0)
	v_add_f32_e32 v5, v3, v7
	ds_bpermute_b32 v2, v20, v0
	ds_bpermute_b32 v3, v25, v1
	ds_bpermute_b32 v6, v30, v4
	ds_bpermute_b32 v7, v8, v5
	v_bitop3_b32 v10, v10, 4, v211 bitop3:0x6c
	v_bitop3_b32 v11, v11, 4, v211 bitop3:0x6c
	v_bitop3_b32 v14, v14, 4, v211 bitop3:0x6c
	v_bitop3_b32 v8, v15, 4, v211 bitop3:0x6c
	s_waitcnt lgkmcnt(3)
	v_add_f32_e32 v2, v0, v2
	s_waitcnt lgkmcnt(2)
	v_add_f32_e32 v0, v1, v3
	s_waitcnt lgkmcnt(1)
	v_add_f32_e32 v3, v4, v6
	s_waitcnt lgkmcnt(0)
	v_add_f32_e32 v4, v5, v7
	ds_bpermute_b32 v7, v10, v2
	ds_bpermute_b32 v1, v11, v0
	ds_bpermute_b32 v5, v14, v3
	ds_bpermute_b32 v6, v8, v4
	s_and_saveexec_b64 s[64:65], s[4:5]
	s_cbranch_execz .LBB0_647
	s_waitcnt lgkmcnt(3)
	v_add_f32_e32 v2, v2, v7
	v_cmp_lt_i32_e64 s[6:7], 0, v117
	s_and_saveexec_b64 s[66:67], s[6:7]
	s_cbranch_execz .LBB0_646
	v_cmp_ne_u32_e64 s[6:7], 1, v117
	s_and_saveexec_b64 s[38:39], s[6:7]
	s_xor_b64 s[6:7], exec, s[38:39]
	s_cbranch_execz .LBB0_643
	s_waitcnt lgkmcnt(1)
	v_add_f32_e32 v0, v3, v5
	s_waitcnt lgkmcnt(0)
	v_add_f32_e32 v1, v4, v6
	v_cndmask_b32_e32 v2, v1, v0, vcc

; DI unsigned pk2(float a, float b) { f2_t v = {a, b}; bf2_t r = __builtin_convertvector(v, bf2_t); return __builtin_bit_cast(unsigned, r); }
; template <int WHICH>
; DI void norm_item(const CP& p, int l, int item) {
;     ...
;   for (int it = 0; it < 4; ++it) {
;     const int t = item * 32 + w * 4 + it;
;     const int b = t / S_;
;     fl4 xv[4];
;     float ssq = 0.f;
; #pragma unroll
;     for (int q = 0; q < 4; ++q) {
;       xv[q] = *(const fl4*)(xs + (size_t)t * 1024 + q * 256 + lane * 4);
;       ssq += xv[q].x * xv[q].x + xv[q].y * xv[q].y + xv[q].z * xv[q].z + xv[q].w * xv[q].w;
;     }
;     ssq = wave_sum(ssq);
;     const float rstd = __builtin_amdgcn_rsqf(ssq * (1.f / 1024.f) + 1e-6f);
;     if (WHICH == 3) {
; #pragma unroll
;       for (int q = 0; q < 4; ++q) {
;         fl4 g = *(const fl4*)(gain + q * 256 + lane * 4);
;         fl4 o;
;         o.x = xv[q].x * rstd * g.x; o.y = xv[q].y * rstd * g.y; o.z = xv[q].z * rstd * g.z; o.w = xv[q].w * rstd * g.w;
;         *(fl4*)(p.out + (size_t)t * 1024 + q * 256 + lane * 4) = o;
;       }
;     } else {
;       const float* md = p.mod + ((size_t)l * 2 + b) * 6144 + (WHICH == 1 ? 0 : 3072);
;       float f0 = 0.f, f1 = 0.f, f2 = 0.f, f3 = 0.f;
; #pragma unroll
;       for (int q = 0; q < 4; ++q) {
;         const int col = q * 256 + lane * 4;
;         fl4 g = *(const fl4*)(gain + col);
;         fl4 sh = *(const fl4*)(md + col);
;         fl4 sc = *(const fl4*)(md + 1024 + col);
;         fl4 h;
;         h.x = xv[q].x * rstd * g.x * (1.f + sc.x) + sh.x;
;         h.y = xv[q].y * rstd * g.y * (1.f + sc.y) + sh.y;
;         h.z = xv[q].z * rstd * g.z * (1.f + sc.z) + sh.z;
;         h.w = xv[q].w * rstd * g.w * (1.f + sc.w) + sh.w;
;         u32x2 v;
;         v.x = pk2(h.x, h.y); v.y = pk2(h.z, h.w);
;         *(u32x2*)(p.hbuf + (size_t)t * 1024 + col) = v;
;         if (WHICH == 1) {
;           const float* wf = p.wf + (size_t)l * 4096 + col;
;           fl4 w0 = *(const fl4*)(wf), w1 = *(const fl4*)(wf + 1024), w2 = *(const fl4*)(wf + 2048), w3 = *(const fl4*)(wf + 3072);
;           f0 += h.x * w0.x + h.y * w0.y + h.z * w0.z + h.w * w0.w;
;           f1 += h.x * w1.x + h.y * w1.y + h.z * w1.z + h.w * w1.w;
;           f2 += h.x * w2.x + h.y * w2.y + h.z * w2.z + h.w * w2.w;
;           f3 += h.x * w3.x + h.y * w3.y + h.z * w3.z + h.w * w3.w;
;         }
.LBB0_647:
	s_or_b64 exec, exec, s[64:65]
	v_add_u32_e32 v16, 2, v66
	v_ashrrev_i32_e32 v17, 31, v16
	s_waitcnt lgkmcnt(2)
	v_lshlrev_b64 v[0:1], 12, v[16:17]
	v_lshl_add_u64 v[0:1], v[70:71], 0, v[0:1]
	v_mov_b64_e32 v[12:13], v[184:185]
	v_mov_b64_e32 v[14:15], v[186:187]
	v_mov_b64_e32 v[8:9], v[188:189]
	v_mov_b64_e32 v[10:11], v[190:191]
	s_waitcnt lgkmcnt(0)
	v_mov_b64_e32 v[4:5], v[192:193]
	v_mov_b64_e32 v[6:7], v[194:195]
	s_nop 0
	v_mov_b64_e32 v[0:1], v[196:197]
	v_mov_b64_e32 v[2:3], v[198:199]
	v_lshrrev_b32_e32 v20, 18, v17
	v_add_u32_e32 v20, v16, v20
	v_ashrrev_i32_e32 v110, 14, v20
	v_ashrrev_i32_e32 v111, 31, v110
	v_mov_b64_e32 v[18:19], s[14:15]
	v_lshl_add_u64 v[20:21], s[28:29], 0, v[110:111]
	v_mad_u64_u32 v[22:23], s[6:7], v20, s93, v[18:19]
	v_mad_i32_i24 v23, v21, s93, v23
	v_lshl_add_u64 v[26:27], v[22:23], 0, s[60:61]
	v_mov_b32_e32 v38, v202
	v_lshl_add_u64 v[18:19], v[26:27], 0, v[32:33]
	global_load_dwordx4 v[18:21], v[18:19], off
	s_nop 0
	global_load_dwordx4 v[28:31], v[94:95], off
	v_lshl_add_u64 v[24:25], v[22:23], 0, v[32:33]
	global_load_dwordx4 v[34:37], v[24:25], off
	v_lshlrev_b32_e32 v44, 2, v38
	v_bitop3_b32 v45, v44, s84, v211 bitop3:0x6c
	v_lshlrev_b64 v[16:17], 11, v[16:17]
	v_mov_b32_e32 v109, v33
	v_lshl_add_u64 v[16:17], s[30:31], 0, v[16:17]
	v_lshl_add_u64 v[112:113], v[16:17], 0, v[108:109]
	v_mov_b32_e32 v73, v33
	v_mov_b32_e32 v75, v33
	v_mov_b32_e32 v77, v33
	v_mov_b32_e32 v109, v202
	s_waitcnt vmcnt(6)
	v_mul_f32_e32 v46, v13, v13
	s_waitcnt vmcnt(5)
	v_mul_f32_e32 v47, v9, v9
	s_waitcnt vmcnt(4)
	v_mov_b32_e32 v38, v5
	s_waitcnt vmcnt(3)
	v_mov_b32_e32 v39, v1
	v_mov_b32_e32 v22, v4
	v_mov_b32_e32 v23, v0
	v_fmac_f32_e32 v46, v12, v12
	v_fmac_f32_e32 v47, v8, v8
	v_pk_mul_f32 v[38:39], v[38:39], v[38:39]
	v_mov_b32_e32 v40, v6
	v_mov_b32_e32 v41, v2
	v_fmac_f32_e32 v46, v14, v14
	v_fmac_f32_e32 v47, v10, v10
	v_pk_fma_f32 v[22:23], v[22:23], v[22:23], v[38:39]
	v_mov_b32_e32 v42, v7
	v_mov_b32_e32 v43, v3
	v_fmac_f32_e32 v46, v15, v15
	v_fmac_f32_e32 v47, v11, v11
	v_pk_fma_f32 v[22:23], v[40:41], v[40:41], v[22:23]
	v_add_f32_e32 v38, v46, v47
	v_pk_fma_f32 v[22:23], v[42:43], v[42:43], v[22:23]
	s_waitcnt vmcnt(2)
	v_pk_add_f32 v[18:19], v[18:19], 1.0 op_sel_hi:[1,0]
	v_add_f32_e32 v22, v38, v22
	v_add_f32_e32 v22, v22, v23
	ds_bpermute_b32 v23, v45, v22
	v_bitop3_b32 v38, v44, 64, v211 bitop3:0x6c
	v_pk_add_f32 v[20:21], v[20:21], 1.0 op_sel_hi:[1,0]
	v_lshl_add_u64 v[42:43], v[26:27], 0, v[74:75]
	v_mov_b32_e32 v75, v202
	s_waitcnt lgkmcnt(0)
	v_add_f32_e32 v22, v22, v23
	ds_bpermute_b32 v23, v38, v22
	v_bitop3_b32 v38, v44, 32, v211 bitop3:0x6c
	s_waitcnt lgkmcnt(0)
	v_add_f32_e32 v22, v22, v23
	ds_bpermute_b32 v23, v38, v22
	v_bitop3_b32 v38, v44, 16, v211 bitop3:0x6c
	s_waitcnt lgkmcnt(0)
	v_add_f32_e32 v22, v22, v23
	ds_bpermute_b32 v23, v38, v22
	v_bitop3_b32 v38, v44, 8, v211 bitop3:0x6c
	s_waitcnt lgkmcnt(0)
	v_add_f32_e32 v22, v22, v23
	ds_bpermute_b32 v23, v38, v22
	v_bitop3_b32 v38, v44, 4, v211 bitop3:0x6c
	s_waitcnt lgkmcnt(0)
	v_add_f32_e32 v22, v22, v23
	ds_bpermute_b32 v23, v38, v22
	s_waitcnt lgkmcnt(0)
	v_add_f32_e32 v16, v22, v23
	v_fmamk_f32 v16, v16, 0x3a800000, v203
	v_rsq_f32_e32 v116, v16
	v_lshl_add_u64 v[16:17], v[26:27], 0, v[72:73]
	v_lshl_add_u64 v[26:27], v[26:27], 0, v[76:77]
	v_mov_b32_e32 v73, v202
	v_pk_mul_f32 v[12:13], v[12:13], v[116:117] op_sel_hi:[1,0]
	v_pk_mul_f32 v[14:15], v[14:15], v[116:117] op_sel_hi:[1,0]
	s_waitcnt vmcnt(1)
	v_pk_mul_f32 v[12:13], v[28:29], v[12:13]
	v_pk_mul_f32 v[14:15], v[30:31], v[14:15]
	s_waitcnt vmcnt(0)
	v_pk_fma_f32 v[118:119], v[18:19], v[12:13], v[34:35]
	v_pk_fma_f32 v[114:115], v[20:21], v[14:15], v[36:37]
	v_cvt_pk_bf16_f32 v12, v118, v119
	v_cvt_pk_bf16_f32 v13, v114, v115
	global_store_dwordx2 v[112:113], v[12:13], off
	global_load_dwordx4 v[28:31], v[94:95], off offset:1024
	global_load_dwordx4 v[34:37], v[16:17], off
	global_load_dwordx4 v[38:41], v[24:25], off offset:1024
	v_pk_mul_f32 v[44:45], v[8:9], v[116:117] op_sel_hi:[1,0]
	v_pk_mul_f32 v[46:47], v[10:11], v[116:117] op_sel_hi:[1,0]
	global_load_dwordx4 v[8:11], v[68:69], off
	global_load_dwordx4 v[12:15], v[102:103], off
	global_load_dwordx4 v[16:19], v[104:105], off
	global_load_dwordx4 v[20:23], v[106:107], off
	v_pk_mul_f32 v[4:5], v[4:5], v[116:117] op_sel_hi:[1,0]
	v_pk_mul_f32 v[6:7], v[6:7], v[116:117] op_sel_hi:[1,0]
	v_pk_mul_f32 v[0:1], v[0:1], v[116:117] op_sel_hi:[1,0]
	v_pk_mul_f32 v[2:3], v[2:3], v[116:117] op_sel_hi:[1,0]
	v_mov_b32_e32 v77, v202
	s_waitcnt vmcnt(6)
	v_pk_mul_f32 v[28:29], v[44:45], v[28:29]
	s_waitcnt vmcnt(5)
	v_pk_add_f32 v[34:35], v[34:35], 1.0 op_sel_hi:[1,0]
	v_pk_mul_f32 v[30:31], v[46:47], v[30:31]
	v_pk_add_f32 v[36:37], v[36:37], 1.0 op_sel_hi:[1,0]
	s_waitcnt vmcnt(4)
	v_pk_fma_f32 v[122:123], v[28:29], v[34:35], v[38:39]
	v_pk_fma_f32 v[120:121], v[30:31], v[36:37], v[40:41]
	v_cvt_pk_bf16_f32 v28, v122, v123
	v_cvt_pk_bf16_f32 v29, v120, v121
	global_store_dwordx2 v[112:113], v[28:29], off offset:512
	global_load_dwordx4 v[28:31], v[94:95], off offset:2048
	s_nop 0
	global_load_dwordx4 v[34:37], v[42:43], off
	global_load_dwordx4 v[54:57], v[24:25], off offset:2048
	global_load_dwordx4 v[38:41], v[68:69], off offset:1024
	s_nop 0
	global_load_dwordx4 v[42:45], v[96:97], off
	global_load_dwordx4 v[46:49], v[98:99], off
	global_load_dwordx4 v[50:53], v[100:101], off
	s_waitcnt vmcnt(11)
	v_mul_f32_e32 v116, v9, v119
	s_waitcnt vmcnt(10)
	v_mul_f32_e32 v128, v13, v119
	v_fmac_f32_e32 v116, v8, v118
	v_fmac_f32_e32 v128, v12, v118
	s_waitcnt vmcnt(9)
; DI unsigned pk2(float a, float b) { f2_t v = {a, b}; bf2_t r = __builtin_convertvector(v, bf2_t); return __builtin_bit_cast(unsigned, r); }
; template <int WHICH>
; DI void norm_item(const CP& p, int l, int item) {
;     ...
; #pragma unroll
;       for (int q = 0; q < 4; ++q) {
;         const int col = q * 256 + lane * 4;
;         fl4 g = *(const fl4*)(gain + col);
;         fl4 sh = *(const fl4*)(md + col);
;         fl4 sc = *(const fl4*)(md + 1024 + col);
;         fl4 h;
;         h.x = xv[q].x * rstd * g.x * (1.f + sc.x) + sh.x;
;         h.y = xv[q].y * rstd * g.y * (1.f + sc.y) + sh.y;
;         h.z = xv[q].z * rstd * g.z * (1.f + sc.z) + sh.z;
;         h.w = xv[q].w * rstd * g.w * (1.f + sc.w) + sh.w;
;         u32x2 v;
;         v.x = pk2(h.x, h.y); v.y = pk2(h.z, h.w);
;         *(u32x2*)(p.hbuf + (size_t)t * 1024 + col) = v;
;         if (WHICH == 1) {
;           const float* wf = p.wf + (size_t)l * 4096 + col;
;           fl4 w0 = *(const fl4*)(wf), w1 = *(const fl4*)(wf + 1024), w2 = *(const fl4*)(wf + 2048), w3 = *(const fl4*)(wf + 3072);
;           f0 += h.x * w0.x + h.y * w0.y + h.z * w0.z + h.w * w0.w;
;           f1 += h.x * w1.x + h.y * w1.y + h.z * w1.z + h.w * w1.w;
;           f2 += h.x * w2.x + h.y * w2.y + h.z * w2.z + h.w * w2.w;
;           f3 += h.x * w3.x + h.y * w3.y + h.z * w3.z + h.w * w3.w;
;         }
;       }
;       if (WHICH == 1) {
;         f0 = wave_sum(f0); f1 = wave_sum(f1); f2 = wave_sum(f2); f3 = wave_sum(f3);
;         if (lane < 4) {
;           float f = lane == 0 ? f0 : (lane == 1 ? f1 : (lane == 2 ? f2 : f3));
	v_mul_f32_e32 v17, v17, v119
	v_fmac_f32_e32 v17, v16, v118
	v_fmac_f32_e32 v17, v18, v114
	v_fmac_f32_e32 v17, v19, v115
	v_fmac_f32_e32 v128, v14, v114
	v_add_f32_e32 v14, 0, v17
	v_fmac_f32_e32 v116, v10, v114
	s_waitcnt vmcnt(8)
	v_mul_f32_e32 v21, v21, v119
	v_fmac_f32_e32 v116, v11, v115
	v_fmac_f32_e32 v128, v15, v115
	v_fmac_f32_e32 v21, v20, v118
	v_add_f32_e32 v10, 0, v116
	v_add_f32_e32 v11, 0, v128
	v_fmac_f32_e32 v21, v22, v114
	v_fmac_f32_e32 v21, v23, v115
	v_add_f32_e32 v15, 0, v21
	s_waitcnt vmcnt(3)
	v_mul_f32_e32 v16, v39, v123
	v_pk_mul_f32 v[4:5], v[4:5], v[28:29]
	v_pk_add_f32 v[28:29], v[34:35], 1.0 op_sel_hi:[1,0]
	v_pk_mul_f32 v[6:7], v[6:7], v[30:31]
	v_pk_add_f32 v[30:31], v[36:37], 1.0 op_sel_hi:[1,0]
	v_pk_fma_f32 v[126:127], v[4:5], v[28:29], v[54:55]
	v_pk_fma_f32 v[124:125], v[6:7], v[30:31], v[56:57]
	v_cvt_pk_bf16_f32 v4, v126, v127
	v_cvt_pk_bf16_f32 v5, v124, v125
	global_store_dwordx2 v[112:113], v[4:5], off offset:1024
	global_load_dwordx4 v[58:61], v[94:95], off offset:3072
	global_load_dwordx4 v[62:65], v[26:27], off
	global_load_dwordx4 v[54:57], v[24:25], off offset:3072
	s_nop 0
	global_load_dwordx4 v[4:7], v[68:69], off offset:2048
	global_load_dwordx4 v[24:27], v[88:89], off
	global_load_dwordx4 v[28:31], v[90:91], off
	global_load_dwordx4 v[34:37], v[92:93], off
	s_waitcnt vmcnt(10)
	v_mul_f32_e32 v17, v123, v43
	s_waitcnt vmcnt(9)
	v_mul_f32_e32 v18, v123, v47
	v_fmac_f32_e32 v16, v38, v122
	v_fmac_f32_e32 v17, v122, v42
	v_fmac_f32_e32 v18, v122, v46
	v_fmac_f32_e32 v16, v40, v120
	v_fmac_f32_e32 v17, v120, v44
	v_fmac_f32_e32 v18, v120, v48
	s_waitcnt vmcnt(8)
	v_mul_f32_e32 v19, v123, v51
	v_fmac_f32_e32 v16, v41, v121
	v_fmac_f32_e32 v17, v121, v45
	v_fmac_f32_e32 v18, v121, v49
	v_fmac_f32_e32 v19, v122, v50
	v_add_f32_e32 v10, v10, v16
	v_add_f32_e32 v11, v11, v17
	v_add_f32_e32 v14, v14, v18
	v_fmac_f32_e32 v19, v120, v52
	v_fmac_f32_e32 v19, v121, v53
	v_add_f32_e32 v15, v15, v19
	s_waitcnt vmcnt(6)
	v_pk_mul_f32 v[0:1], v[0:1], v[58:59]
	s_waitcnt vmcnt(5)
	v_pk_add_f32 v[8:9], v[62:63], 1.0 op_sel_hi:[1,0]
	v_pk_mul_f32 v[2:3], v[2:3], v[60:61]
	v_pk_add_f32 v[12:13], v[64:65], 1.0 op_sel_hi:[1,0]
	s_waitcnt vmcnt(4)
	v_pk_fma_f32 v[8:9], v[0:1], v[8:9], v[54:55]
	v_pk_fma_f32 v[12:13], v[2:3], v[12:13], v[56:57]
	v_cvt_pk_bf16_f32 v0, v8, v9
	v_cvt_pk_bf16_f32 v1, v12, v13
	global_store_dwordx2 v[112:113], v[0:1], off offset:1536
	global_load_dwordx4 v[0:3], v[68:69], off offset:3072
	s_nop 0
	global_load_dwordx4 v[54:57], v[82:83], off
	global_load_dwordx4 v[58:61], v[84:85], off
	global_load_dwordx4 v[62:65], v[86:87], off
	s_waitcnt vmcnt(8)
	v_mul_f32_e32 v5, v5, v127
	s_waitcnt vmcnt(7)
	v_mul_f32_e32 v16, v127, v25
	s_waitcnt vmcnt(6)
	v_mul_f32_e32 v17, v127, v29
	s_waitcnt vmcnt(5)
	v_mul_f32_e32 v18, v127, v35
	v_fmac_f32_e32 v5, v4, v126
	v_fmac_f32_e32 v16, v126, v24
	v_fmac_f32_e32 v17, v126, v28
	v_fmac_f32_e32 v18, v126, v34
	v_fmac_f32_e32 v5, v6, v124
	v_fmac_f32_e32 v16, v124, v26
	v_fmac_f32_e32 v17, v124, v30
	v_fmac_f32_e32 v18, v124, v36
	v_fmac_f32_e32 v5, v7, v125
	v_fmac_f32_e32 v16, v125, v27
	v_fmac_f32_e32 v17, v125, v31
	v_fmac_f32_e32 v18, v125, v37
	v_add_f32_e32 v4, v10, v5
	v_add_f32_e32 v5, v11, v16
	v_add_f32_e32 v6, v14, v17
	v_add_f32_e32 v7, v15, v18
	s_waitcnt vmcnt(3)
	v_mul_f32_e32 v1, v1, v9
	s_waitcnt vmcnt(2)
	v_mul_f32_e32 v34, v9, v55
	s_waitcnt vmcnt(1)
	v_mul_f32_e32 v35, v9, v59
	s_waitcnt vmcnt(0)
	v_mul_f32_e32 v9, v9, v63
	v_fmac_f32_e32 v1, v0, v8
	v_fmac_f32_e32 v34, v8, v54
	v_fmac_f32_e32 v35, v8, v58
	v_fmac_f32_e32 v9, v8, v62
	v_fmac_f32_e32 v1, v2, v12
	v_fmac_f32_e32 v34, v12, v56
	v_fmac_f32_e32 v35, v12, v60
	v_fmac_f32_e32 v9, v12, v64
	v_lshlrev_b32_e32 v10, 2, v73
	v_lshlrev_b32_e32 v11, 2, v75
	v_lshlrev_b32_e32 v14, 2, v77
	v_lshlrev_b32_e32 v15, 2, v109
	v_fmac_f32_e32 v1, v3, v13
	v_fmac_f32_e32 v34, v13, v57
	v_fmac_f32_e32 v35, v13, v61
	v_fmac_f32_e32 v9, v13, v65
	v_bitop3_b32 v16, v10, s84, v211 bitop3:0x6c
	v_bitop3_b32 v21, v11, s84, v211 bitop3:0x6c
	v_bitop3_b32 v26, v14, s84, v211 bitop3:0x6c
	v_bitop3_b32 v31, v15, s84, v211 bitop3:0x6c
	v_add_f32_e32 v0, v4, v1
	v_add_f32_e32 v1, v5, v34
	v_add_f32_e32 v2, v6, v35
	v_add_f32_e32 v3, v7, v9
	ds_bpermute_b32 v4, v16, v0
	ds_bpermute_b32 v5, v21, v1
	ds_bpermute_b32 v6, v26, v2
	ds_bpermute_b32 v7, v31, v3
	v_bitop3_b32 v17, v10, 64, v211 bitop3:0x6c
	v_bitop3_b32 v22, v11, 64, v211 bitop3:0x6c
	v_bitop3_b32 v27, v14, 64, v211 bitop3:0x6c
	v_bitop3_b32 v8, v15, 64, v211 bitop3:0x6c
	s_waitcnt lgkmcnt(3)
	v_add_f32_e32 v0, v0, v4
	s_waitcnt lgkmcnt(2)
	v_add_f32_e32 v1, v1, v5
	s_waitcnt lgkmcnt(1)
	v_add_f32_e32 v2, v2, v6
	s_waitcnt lgkmcnt(0)
	v_add_f32_e32 v3, v3, v7
	ds_bpermute_b32 v4, v17, v0
	ds_bpermute_b32 v5, v22, v1
	ds_bpermute_b32 v6, v27, v2
	ds_bpermute_b32 v7, v8, v3
	v_bitop3_b32 v18, v10, 32, v211 bitop3:0x6c
	v_bitop3_b32 v23, v11, 32, v211 bitop3:0x6c
	v_bitop3_b32 v28, v14, 32, v211 bitop3:0x6c
	v_bitop3_b32 v8, v15, 32, v211 bitop3:0x6c
	s_waitcnt lgkmcnt(3)
	v_add_f32_e32 v0, v0, v4
	s_waitcnt lgkmcnt(2)
	v_add_f32_e32 v1, v1, v5
	s_waitcnt lgkmcnt(1)
	v_add_f32_e32 v2, v2, v6
	s_waitcnt lgkmcnt(0)
	v_add_f32_e32 v3, v3, v7
	ds_bpermute_b32 v4, v18, v0
	ds_bpermute_b32 v5, v23, v1
	ds_bpermute_b32 v6, v28, v2
	ds_bpermute_b32 v7, v8, v3
	v_bitop3_b32 v19, v10, 16, v211 bitop3:0x6c
	v_bitop3_b32 v24, v11, 16, v211 bitop3:0x6c
	v_bitop3_b32 v29, v14, 16, v211 bitop3:0x6c
	v_bitop3_b32 v8, v15, 16, v211 bitop3:0x6c
	s_waitcnt lgkmcnt(3)
	v_add_f32_e32 v0, v0, v4
	s_waitcnt lgkmcnt(2)
	v_add_f32_e32 v1, v1, v5
	s_waitcnt lgkmcnt(1)
	v_add_f32_e32 v2, v2, v6
	s_waitcnt lgkmcnt(0)
	v_add_f32_e32 v3, v3, v7
	ds_bpermute_b32 v4, v19, v0
	ds_bpermute_b32 v5, v24, v1
	ds_bpermute_b32 v6, v29, v2
	ds_bpermute_b32 v7, v8, v3
	v_bitop3_b32 v20, v10, 8, v211 bitop3:0x6c
	v_bitop3_b32 v25, v11, 8, v211 bitop3:0x6c
	v_bitop3_b32 v30, v14, 8, v211 bitop3:0x6c
	v_bitop3_b32 v8, v15, 8, v211 bitop3:0x6c
	s_waitcnt lgkmcnt(3)
	v_add_f32_e32 v0, v0, v4
	s_waitcnt lgkmcnt(2)
	v_add_f32_e32 v1, v1, v5
	s_waitcnt lgkmcnt(1)
	v_add_f32_e32 v4, v2, v6
	s_waitcnt lgkmcnt(0)
	v_add_f32_e32 v5, v3, v7
	ds_bpermute_b32 v2, v20, v0
	ds_bpermute_b32 v3, v25, v1
	ds_bpermute_b32 v6, v30, v4
	ds_bpermute_b32 v7, v8, v5
	v_bitop3_b32 v10, v10, 4, v211 bitop3:0x6c
	v_bitop3_b32 v11, v11, 4, v211 bitop3:0x6c
	v_bitop3_b32 v14, v14, 4, v211 bitop3:0x6c
	v_bitop3_b32 v8, v15, 4, v211 bitop3:0x6c
	s_waitcnt lgkmcnt(3)
	v_add_f32_e32 v2, v0, v2
	s_waitcnt lgkmcnt(2)
	v_add_f32_e32 v0, v1, v3
	s_waitcnt lgkmcnt(1)
	v_add_f32_e32 v3, v4, v6
	s_waitcnt lgkmcnt(0)
	v_add_f32_e32 v4, v5, v7
	ds_bpermute_b32 v7, v10, v2
	ds_bpermute_b32 v1, v11, v0
	ds_bpermute_b32 v5, v14, v3
	ds_bpermute_b32 v6, v8, v4
	s_and_saveexec_b64 s[64:65], s[4:5]
	s_cbranch_execz .LBB0_655
; template <int WHICH>
; DI void norm_item(const CP& p, int l, int item) {
;     ...
;       if (WHICH == 1) {
;         f0 = wave_sum(f0); f1 = wave_sum(f1); f2 = wave_sum(f2); f3 = wave_sum(f3);
;         if (lane < 4) {
;           float f = lane == 0 ? f0 : (lane == 1 ? f1 : (lane == 2 ? f2 : f3));
;           float v = f + p.fbias[l * 4 + lane];
	s_waitcnt lgkmcnt(3)
	v_add_f32_e32 v2, v2, v7
	v_cmp_lt_i32_e64 s[6:7], 0, v117
	s_and_saveexec_b64 s[66:67], s[6:7]
	s_cbranch_execz .LBB0_654
	v_cmp_ne_u32_e64 s[6:7], 1, v117
	s_and_saveexec_b64 s[38:39], s[6:7]
	s_xor_b64 s[6:7], exec, s[38:39]
	s_cbranch_execz .LBB0_651
	s_waitcnt lgkmcnt(1)
	v_add_f32_e32 v0, v3, v5
	s_waitcnt lgkmcnt(0)
	v_add_f32_e32 v1, v4, v6
	v_cndmask_b32_e32 v2, v1, v0, vcc

; DI unsigned pk2(float a, float b) { f2_t v = {a, b}; bf2_t r = __builtin_convertvector(v, bf2_t); return __builtin_bit_cast(unsigned, r); }
; template <int WHICH>
; DI void norm_item(const CP& p, int l, int item) {
;     ...
;     for (int q = 0; q < 4; ++q) {
;       xv[q] = *(const fl4*)(xs + (size_t)t * 1024 + q * 256 + lane * 4);
;       ssq += xv[q].x * xv[q].x + xv[q].y * xv[q].y + xv[q].z * xv[q].z + xv[q].w * xv[q].w;
;     }
;     ssq = wave_sum(ssq);
;     const float rstd = __builtin_amdgcn_rsqf(ssq * (1.f / 1024.f) + 1e-6f);
;     if (WHICH == 3) {
; #pragma unroll
;       for (int q = 0; q < 4; ++q) {
;         fl4 g = *(const fl4*)(gain + q * 256 + lane * 4);
;         fl4 o;
;         o.x = xv[q].x * rstd * g.x; o.y = xv[q].y * rstd * g.y; o.z = xv[q].z * rstd * g.z; o.w = xv[q].w * rstd * g.w;
;         *(fl4*)(p.out + (size_t)t * 1024 + q * 256 + lane * 4) = o;
;       }
;     } else {
;       const float* md = p.mod + ((size_t)l * 2 + b) * 6144 + (WHICH == 1 ? 0 : 3072);
;       float f0 = 0.f, f1 = 0.f, f2 = 0.f, f3 = 0.f;
; #pragma unroll
;       for (int q = 0; q < 4; ++q) {
;         const int col = q * 256 + lane * 4;
;         fl4 g = *(const fl4*)(gain + col);
;         fl4 sh = *(const fl4*)(md + col);
;         fl4 sc = *(const fl4*)(md + 1024 + col);
;         fl4 h;
;         h.x = xv[q].x * rstd * g.x * (1.f + sc.x) + sh.x;
;         h.y = xv[q].y * rstd * g.y * (1.f + sc.y) + sh.y;
;         h.z = xv[q].z * rstd * g.z * (1.f + sc.z) + sh.z;
;         h.w = xv[q].w * rstd * g.w * (1.f + sc.w) + sh.w;
;         u32x2 v;
;         v.x = pk2(h.x, h.y); v.y = pk2(h.z, h.w);
;         *(u32x2*)(p.hbuf + (size_t)t * 1024 + col) = v;
;         if (WHICH == 1) {
;           const float* wf = p.wf + (size_t)l * 4096 + col;
;           fl4 w0 = *(const fl4*)(wf), w1 = *(const fl4*)(wf + 1024), w2 = *(const fl4*)(wf + 2048), w3 = *(const fl4*)(wf + 3072);
;           f0 += h.x * w0.x + h.y * w0.y + h.z * w0.z + h.w * w0.w;
;           f1 += h.x * w1.x + h.y * w1.y + h.z * w1.z + h.w * w1.w;
;           f2 += h.x * w2.x + h.y * w2.y + h.z * w2.z + h.w * w2.w;
;           f3 += h.x * w3.x + h.y * w3.y + h.z * w3.z + h.w * w3.w;
.LBB0_655:
	s_or_b64 exec, exec, s[64:65]
	v_add_u32_e32 v16, 3, v66
	v_ashrrev_i32_e32 v17, 31, v16
	s_waitcnt lgkmcnt(2)
	v_lshlrev_b64 v[0:1], 12, v[16:17]
	v_lshl_add_u64 v[0:1], v[70:71], 0, v[0:1]
	v_mov_b64_e32 v[12:13], v[216:217]
	v_mov_b64_e32 v[14:15], v[218:219]
	v_mov_b64_e32 v[8:9], v[220:221]
	v_mov_b64_e32 v[10:11], v[222:223]
	s_waitcnt lgkmcnt(0)
	v_mov_b64_e32 v[4:5], v[224:225]
	v_mov_b64_e32 v[6:7], v[226:227]
	s_nop 0
	v_mov_b64_e32 v[0:1], v[228:229]
	v_mov_b64_e32 v[2:3], v[230:231]
	v_lshrrev_b32_e32 v20, 18, v17
	v_add_u32_e32 v20, v16, v20
	v_ashrrev_i32_e32 v54, 14, v20
	v_ashrrev_i32_e32 v55, 31, v54
	v_mov_b64_e32 v[18:19], s[14:15]
	v_lshl_add_u64 v[20:21], s[28:29], 0, v[54:55]
	v_mad_u64_u32 v[22:23], s[6:7], v20, s93, v[18:19]
	v_mad_i32_i24 v23, v21, s93, v23
	v_lshl_add_u64 v[24:25], v[22:23], 0, s[60:61]
	v_mov_b32_e32 v30, v202
	v_lshl_add_u64 v[18:19], v[24:25], 0, v[32:33]
	global_load_dwordx4 v[18:21], v[18:19], off
	s_nop 0
	global_load_dwordx4 v[26:29], v[94:95], off
	v_lshl_add_u64 v[38:39], v[22:23], 0, v[32:33]
	global_load_dwordx4 v[34:37], v[38:39], off
	v_lshlrev_b32_e32 v32, 2, v30
	v_bitop3_b32 v44, v32, s84, v211 bitop3:0x6c
	v_lshlrev_b64 v[16:17], 11, v[16:17]
	v_mov_b32_e32 v109, v33
	v_lshl_add_u64 v[16:17], s[30:31], 0, v[16:17]
	v_lshl_add_u64 v[56:57], v[16:17], 0, v[108:109]
	v_mov_b32_e32 v73, v33
	v_mov_b32_e32 v75, v33
	v_mov_b32_e32 v77, v33
	v_lshl_add_u64 v[52:53], v[24:25], 0, v[76:77]
	s_waitcnt vmcnt(6)
	v_mul_f32_e32 v45, v13, v13
	s_waitcnt vmcnt(5)
	v_mul_f32_e32 v46, v9, v9
	s_waitcnt vmcnt(4)
	v_mov_b32_e32 v30, v5
	s_waitcnt vmcnt(3)
	v_mov_b32_e32 v31, v1
	v_mov_b32_e32 v22, v4
	v_mov_b32_e32 v23, v0
	v_fmac_f32_e32 v45, v12, v12
	v_fmac_f32_e32 v46, v8, v8
	v_pk_mul_f32 v[30:31], v[30:31], v[30:31]
	v_mov_b32_e32 v40, v6
	v_mov_b32_e32 v41, v2
	v_fmac_f32_e32 v45, v14, v14
	v_fmac_f32_e32 v46, v10, v10
	v_pk_fma_f32 v[22:23], v[22:23], v[22:23], v[30:31]
	v_mov_b32_e32 v42, v7
	v_mov_b32_e32 v43, v3
	v_fmac_f32_e32 v45, v15, v15
	v_fmac_f32_e32 v46, v11, v11
	v_pk_fma_f32 v[22:23], v[40:41], v[40:41], v[22:23]
	v_add_f32_e32 v30, v45, v46
	v_pk_fma_f32 v[22:23], v[42:43], v[42:43], v[22:23]
	s_waitcnt vmcnt(2)
	v_pk_add_f32 v[18:19], v[18:19], 1.0 op_sel_hi:[1,0]
	v_add_f32_e32 v22, v30, v22
	v_add_f32_e32 v22, v22, v23
	ds_bpermute_b32 v23, v44, v22
	v_bitop3_b32 v30, v32, 64, v211 bitop3:0x6c
	v_pk_add_f32 v[20:21], v[20:21], 1.0 op_sel_hi:[1,0]
	s_waitcnt lgkmcnt(0)
	v_add_f32_e32 v22, v22, v23
	ds_bpermute_b32 v23, v30, v22
	v_bitop3_b32 v30, v32, 32, v211 bitop3:0x6c
	s_waitcnt lgkmcnt(0)
	v_add_f32_e32 v22, v22, v23
	ds_bpermute_b32 v23, v30, v22
	v_bitop3_b32 v30, v32, 16, v211 bitop3:0x6c
	s_waitcnt lgkmcnt(0)
	v_add_f32_e32 v22, v22, v23
	ds_bpermute_b32 v23, v30, v22
	v_bitop3_b32 v30, v32, 8, v211 bitop3:0x6c
	s_waitcnt lgkmcnt(0)
	v_add_f32_e32 v22, v22, v23
	ds_bpermute_b32 v23, v30, v22
	v_bitop3_b32 v30, v32, 4, v211 bitop3:0x6c
	s_waitcnt lgkmcnt(0)
	v_add_f32_e32 v22, v22, v23
	ds_bpermute_b32 v23, v30, v22
	v_lshl_add_u64 v[30:31], v[24:25], 0, v[74:75]
	s_waitcnt lgkmcnt(0)
	v_add_f32_e32 v16, v22, v23
	v_fmamk_f32 v16, v16, 0x3a800000, v203
	v_rsq_f32_e32 v32, v16
	v_lshl_add_u64 v[16:17], v[24:25], 0, v[72:73]
	v_pk_mul_f32 v[12:13], v[12:13], v[32:33] op_sel_hi:[1,0]
	v_pk_mul_f32 v[14:15], v[14:15], v[32:33] op_sel_hi:[1,0]
	s_waitcnt vmcnt(1)
	v_pk_mul_f32 v[12:13], v[26:27], v[12:13]
	v_pk_mul_f32 v[14:15], v[28:29], v[14:15]
	s_waitcnt vmcnt(0)
	v_pk_fma_f32 v[60:61], v[18:19], v[12:13], v[34:35]
	v_pk_fma_f32 v[58:59], v[20:21], v[14:15], v[36:37]
	v_cvt_pk_bf16_f32 v12, v60, v61
	v_cvt_pk_bf16_f32 v13, v58, v59
	global_store_dwordx2 v[56:57], v[12:13], off
	global_load_dwordx4 v[26:29], v[94:95], off offset:1024
	global_load_dwordx4 v[34:37], v[16:17], off
	global_load_dwordx4 v[40:43], v[38:39], off offset:1024
	v_pk_mul_f32 v[44:45], v[8:9], v[32:33] op_sel_hi:[1,0]
	v_pk_mul_f32 v[46:47], v[10:11], v[32:33] op_sel_hi:[1,0]
	global_load_dwordx4 v[8:11], v[68:69], off
	global_load_dwordx4 v[12:15], v[102:103], off
	global_load_dwordx4 v[16:19], v[104:105], off
	global_load_dwordx4 v[20:23], v[106:107], off
	v_pk_mul_f32 v[70:71], v[4:5], v[32:33] op_sel_hi:[1,0]
	v_pk_mul_f32 v[72:73], v[6:7], v[32:33] op_sel_hi:[1,0]
	v_pk_mul_f32 v[0:1], v[0:1], v[32:33] op_sel_hi:[1,0]
	v_pk_mul_f32 v[2:3], v[2:3], v[32:33] op_sel_hi:[1,0]
	s_waitcnt vmcnt(6)
	v_pk_mul_f32 v[26:27], v[44:45], v[26:27]
	s_waitcnt vmcnt(5)
	v_pk_add_f32 v[34:35], v[34:35], 1.0 op_sel_hi:[1,0]
	v_pk_mul_f32 v[28:29], v[46:47], v[28:29]
	v_pk_add_f32 v[36:37], v[36:37], 1.0 op_sel_hi:[1,0]
	s_waitcnt vmcnt(4)
	v_pk_fma_f32 v[64:65], v[26:27], v[34:35], v[40:41]
	v_pk_fma_f32 v[62:63], v[28:29], v[36:37], v[42:43]
	v_cvt_pk_bf16_f32 v26, v64, v65
	v_cvt_pk_bf16_f32 v27, v62, v63
	global_store_dwordx2 v[56:57], v[26:27], off offset:512
	global_load_dwordx4 v[40:43], v[94:95], off offset:2048
	global_load_dwordx4 v[44:47], v[30:31], off
	global_load_dwordx4 v[48:51], v[38:39], off offset:2048
	global_load_dwordx4 v[4:7], v[68:69], off offset:1024
	s_nop 0
	global_load_dwordx4 v[24:27], v[96:97], off
	global_load_dwordx4 v[28:31], v[98:99], off
	global_load_dwordx4 v[34:37], v[100:101], off
	s_waitcnt vmcnt(11)
	v_mul_f32_e32 v32, v9, v61
	s_waitcnt vmcnt(10)
	v_mul_f32_e32 v102, v13, v61
	v_fmac_f32_e32 v32, v8, v60
	v_fmac_f32_e32 v102, v12, v60
	s_waitcnt vmcnt(9)
	v_mul_f32_e32 v17, v17, v61
	v_fmac_f32_e32 v17, v16, v60
	v_fmac_f32_e32 v17, v18, v58
	s_waitcnt vmcnt(8)
; template <int WHICH>
; DI void norm_item(const CP& p, int l, int item) {
;     ...
;           const float* wf = p.wf + (size_t)l * 4096 + col;
;           fl4 w0 = *(const fl4*)(wf), w1 = *(const fl4*)(wf + 1024), w2 = *(const fl4*)(wf + 2048), w3 = *(const fl4*)(wf + 3072);
;           f0 += h.x * w0.x + h.y * w0.y + h.z * w0.z + h.w * w0.w;
;           f1 += h.x * w1.x + h.y * w1.y + h.z * w1.z + h.w * w1.w;
;           f2 += h.x * w2.x + h.y * w2.y + h.z * w2.z + h.w * w2.w;
;           f3 += h.x * w3.x + h.y * w3.y + h.z * w3.z + h.w * w3.w;
;         }
;       }
;       if (WHICH == 1) {
;         f0 = wave_sum(f0); f1 = wave_sum(f1); f2 = wave_sum(f2); f3 = wave_sum(f3);
	v_mul_f32_e32 v21, v21, v61
	v_fmac_f32_e32 v17, v19, v59
	v_fmac_f32_e32 v21, v20, v60
	v_fmac_f32_e32 v102, v14, v58
	v_add_f32_e32 v14, 0, v17
	v_fmac_f32_e32 v32, v10, v58
	v_fmac_f32_e32 v21, v22, v58
	v_fmac_f32_e32 v32, v11, v59
	v_fmac_f32_e32 v102, v15, v59
	v_fmac_f32_e32 v21, v23, v59
	v_add_f32_e32 v10, 0, v32
	v_add_f32_e32 v11, 0, v102
	v_add_f32_e32 v15, 0, v21
	s_waitcnt vmcnt(3)
	v_mul_f32_e32 v5, v5, v65
	v_pk_mul_f32 v[40:41], v[70:71], v[40:41]
	v_pk_add_f32 v[44:45], v[44:45], 1.0 op_sel_hi:[1,0]
	v_pk_mul_f32 v[42:43], v[72:73], v[42:43]
	v_pk_add_f32 v[46:47], v[46:47], 1.0 op_sel_hi:[1,0]
	v_pk_fma_f32 v[72:73], v[40:41], v[44:45], v[48:49]
	v_pk_fma_f32 v[70:71], v[42:43], v[46:47], v[50:51]
	v_cvt_pk_bf16_f32 v40, v72, v73
	v_cvt_pk_bf16_f32 v41, v70, v71
	global_store_dwordx2 v[56:57], v[40:41], off offset:1024
	global_load_dwordx4 v[74:77], v[94:95], off offset:3072
	s_nop 0
	global_load_dwordx4 v[94:97], v[52:53], off
	global_load_dwordx4 v[98:101], v[38:39], off offset:3072
	s_nop 0
	global_load_dwordx4 v[38:41], v[68:69], off offset:2048
	global_load_dwordx4 v[42:45], v[88:89], off
	global_load_dwordx4 v[46:49], v[90:91], off
	global_load_dwordx4 v[50:53], v[92:93], off
	s_waitcnt vmcnt(10)
	v_mul_f32_e32 v16, v65, v25
	s_waitcnt vmcnt(9)
	v_mul_f32_e32 v17, v65, v29
	s_waitcnt vmcnt(8)
	v_mul_f32_e32 v18, v65, v35
	v_fmac_f32_e32 v5, v4, v64
	v_fmac_f32_e32 v16, v64, v24
	v_fmac_f32_e32 v17, v64, v28
	v_fmac_f32_e32 v18, v64, v34
	v_fmac_f32_e32 v5, v6, v62
	v_fmac_f32_e32 v16, v62, v26
	v_fmac_f32_e32 v17, v62, v30
	v_fmac_f32_e32 v18, v62, v36
	v_fmac_f32_e32 v5, v7, v63
	v_fmac_f32_e32 v16, v63, v27
	v_fmac_f32_e32 v17, v63, v31
	v_fmac_f32_e32 v18, v63, v37
	v_add_f32_e32 v4, v10, v5
	v_add_f32_e32 v5, v11, v16
	v_add_f32_e32 v6, v14, v17
	v_add_f32_e32 v7, v15, v18
	v_mov_b32_e32 v90, v202
	v_mov_b32_e32 v91, v202
	v_mov_b32_e32 v92, v202
	v_mov_b32_e32 v93, v202
	s_waitcnt vmcnt(6)
	v_pk_mul_f32 v[0:1], v[0:1], v[74:75]
	s_waitcnt vmcnt(5)
	v_pk_add_f32 v[8:9], v[94:95], 1.0 op_sel_hi:[1,0]
	v_pk_mul_f32 v[2:3], v[2:3], v[76:77]
	v_pk_add_f32 v[12:13], v[96:97], 1.0 op_sel_hi:[1,0]
	s_waitcnt vmcnt(4)
	v_pk_fma_f32 v[8:9], v[0:1], v[8:9], v[98:99]
	v_pk_fma_f32 v[12:13], v[2:3], v[12:13], v[100:101]
	v_cvt_pk_bf16_f32 v0, v8, v9
	v_cvt_pk_bf16_f32 v1, v12, v13
	global_store_dwordx2 v[56:57], v[0:1], off offset:1536
	global_load_dwordx4 v[0:3], v[68:69], off offset:3072
	s_nop 0
	global_load_dwordx4 v[74:77], v[82:83], off
	s_nop 0
	global_load_dwordx4 v[82:85], v[84:85], off
	s_nop 0
	global_load_dwordx4 v[86:89], v[86:87], off
	s_waitcnt vmcnt(8)
	v_mul_f32_e32 v10, v39, v73
	s_waitcnt vmcnt(7)
	v_mul_f32_e32 v11, v73, v43
	s_waitcnt vmcnt(6)
	v_mul_f32_e32 v14, v73, v47
	s_waitcnt vmcnt(5)
	v_mul_f32_e32 v15, v73, v51
	v_fmac_f32_e32 v10, v38, v72
	v_fmac_f32_e32 v11, v72, v42
	v_fmac_f32_e32 v14, v72, v46
	v_fmac_f32_e32 v15, v72, v50
	v_fmac_f32_e32 v10, v40, v70
	v_fmac_f32_e32 v11, v70, v44
	v_fmac_f32_e32 v14, v70, v48
	v_fmac_f32_e32 v15, v70, v52
	v_fmac_f32_e32 v10, v41, v71
	v_fmac_f32_e32 v11, v71, v45
	v_fmac_f32_e32 v14, v71, v49
	v_fmac_f32_e32 v15, v71, v53
	v_add_f32_e32 v4, v4, v10
	v_add_f32_e32 v5, v5, v11
	v_add_f32_e32 v6, v6, v14
	v_add_f32_e32 v7, v7, v15
	s_waitcnt vmcnt(3)
	v_mul_f32_e32 v1, v1, v9
	s_waitcnt vmcnt(2)
	v_mul_f32_e32 v32, v9, v75
	s_waitcnt vmcnt(1)
	v_mul_f32_e32 v34, v9, v83
	s_waitcnt vmcnt(0)
	v_mul_f32_e32 v9, v9, v87
	v_fmac_f32_e32 v1, v0, v8
	v_fmac_f32_e32 v32, v8, v74
	v_fmac_f32_e32 v34, v8, v82
	v_fmac_f32_e32 v9, v8, v86
	v_fmac_f32_e32 v1, v2, v12
	v_fmac_f32_e32 v32, v12, v76
	v_fmac_f32_e32 v34, v12, v84
	v_fmac_f32_e32 v9, v12, v88
	v_lshlrev_b32_e32 v10, 2, v90
	v_lshlrev_b32_e32 v11, 2, v91
	v_lshlrev_b32_e32 v14, 2, v92
	v_lshlrev_b32_e32 v15, 2, v93
	v_fmac_f32_e32 v1, v3, v13
	v_fmac_f32_e32 v32, v13, v77
	v_fmac_f32_e32 v34, v13, v85
	v_fmac_f32_e32 v9, v13, v89
	v_bitop3_b32 v16, v10, s84, v211 bitop3:0x6c
	v_bitop3_b32 v21, v11, s84, v211 bitop3:0x6c
	v_bitop3_b32 v26, v14, s84, v211 bitop3:0x6c
	v_bitop3_b32 v31, v15, s84, v211 bitop3:0x6c
	v_add_f32_e32 v0, v4, v1
	v_add_f32_e32 v1, v5, v32
	v_add_f32_e32 v2, v6, v34
	v_add_f32_e32 v3, v7, v9
	ds_bpermute_b32 v4, v16, v0
	ds_bpermute_b32 v5, v21, v1
	ds_bpermute_b32 v6, v26, v2
	ds_bpermute_b32 v7, v31, v3
	v_bitop3_b32 v17, v10, 64, v211 bitop3:0x6c
	v_bitop3_b32 v22, v11, 64, v211 bitop3:0x6c
	v_bitop3_b32 v27, v14, 64, v211 bitop3:0x6c
	v_bitop3_b32 v8, v15, 64, v211 bitop3:0x6c
	s_waitcnt lgkmcnt(3)
	v_add_f32_e32 v0, v0, v4
	s_waitcnt lgkmcnt(2)
	v_add_f32_e32 v1, v1, v5
	s_waitcnt lgkmcnt(1)
	v_add_f32_e32 v2, v2, v6
	s_waitcnt lgkmcnt(0)
	v_add_f32_e32 v3, v3, v7
	ds_bpermute_b32 v4, v17, v0
	ds_bpermute_b32 v5, v22, v1
	ds_bpermute_b32 v6, v27, v2
	ds_bpermute_b32 v7, v8, v3
	v_bitop3_b32 v18, v10, 32, v211 bitop3:0x6c
	v_bitop3_b32 v23, v11, 32, v211 bitop3:0x6c
	v_bitop3_b32 v28, v14, 32, v211 bitop3:0x6c
	v_bitop3_b32 v8, v15, 32, v211 bitop3:0x6c
	s_waitcnt lgkmcnt(3)
	v_add_f32_e32 v0, v0, v4
	s_waitcnt lgkmcnt(2)
	v_add_f32_e32 v1, v1, v5
	s_waitcnt lgkmcnt(1)
	v_add_f32_e32 v2, v2, v6
	s_waitcnt lgkmcnt(0)
	v_add_f32_e32 v3, v3, v7
	ds_bpermute_b32 v4, v18, v0
	ds_bpermute_b32 v5, v23, v1
	ds_bpermute_b32 v6, v28, v2
	ds_bpermute_b32 v7, v8, v3
	v_bitop3_b32 v19, v10, 16, v211 bitop3:0x6c
	v_bitop3_b32 v24, v11, 16, v211 bitop3:0x6c
	v_bitop3_b32 v29, v14, 16, v211 bitop3:0x6c
	v_bitop3_b32 v8, v15, 16, v211 bitop3:0x6c
	s_waitcnt lgkmcnt(3)
	v_add_f32_e32 v0, v0, v4
	s_waitcnt lgkmcnt(2)
	v_add_f32_e32 v1, v1, v5
	s_waitcnt lgkmcnt(1)
	v_add_f32_e32 v2, v2, v6
	s_waitcnt lgkmcnt(0)
	v_add_f32_e32 v3, v3, v7
	ds_bpermute_b32 v4, v19, v0
	ds_bpermute_b32 v5, v24, v1
	ds_bpermute_b32 v6, v29, v2
	ds_bpermute_b32 v7, v8, v3
	v_bitop3_b32 v20, v10, 8, v211 bitop3:0x6c
	v_bitop3_b32 v25, v11, 8, v211 bitop3:0x6c
	v_bitop3_b32 v30, v14, 8, v211 bitop3:0x6c
	v_bitop3_b32 v8, v15, 8, v211 bitop3:0x6c
	s_waitcnt lgkmcnt(3)
	v_add_f32_e32 v0, v0, v4
	s_waitcnt lgkmcnt(2)
	v_add_f32_e32 v1, v1, v5
	s_waitcnt lgkmcnt(1)
	v_add_f32_e32 v4, v2, v6
	s_waitcnt lgkmcnt(0)
	v_add_f32_e32 v5, v3, v7
	ds_bpermute_b32 v2, v20, v0
	ds_bpermute_b32 v3, v25, v1
	ds_bpermute_b32 v6, v30, v4
	ds_bpermute_b32 v7, v8, v5
	v_bitop3_b32 v10, v10, 4, v211 bitop3:0x6c
	v_bitop3_b32 v11, v11, 4, v211 bitop3:0x6c
	v_bitop3_b32 v14, v14, 4, v211 bitop3:0x6c
	v_bitop3_b32 v8, v15, 4, v211 bitop3:0x6c
	s_waitcnt lgkmcnt(3)
	v_add_f32_e32 v2, v0, v2
	s_waitcnt lgkmcnt(2)
	v_add_f32_e32 v0, v1, v3
	s_waitcnt lgkmcnt(1)
	v_add_f32_e32 v3, v4, v6
	s_waitcnt lgkmcnt(0)
	v_add_f32_e32 v4, v5, v7
	ds_bpermute_b32 v7, v10, v2
	ds_bpermute_b32 v1, v11, v0
	ds_bpermute_b32 v5, v14, v3
	ds_bpermute_b32 v6, v8, v4
	s_and_saveexec_b64 s[6:7], s[4:5]
	s_cbranch_execz .LBB0_620
; template <int WHICH>
; DI void norm_item(const CP& p, int l, int item) {
;     ...
;       if (WHICH == 1) {
;         f0 = wave_sum(f0); f1 = wave_sum(f1); f2 = wave_sum(f2); f3 = wave_sum(f3);
;         if (lane < 4) {
;           float f = lane == 0 ? f0 : (lane == 1 ? f1 : (lane == 2 ? f2 : f3));
;           float v = f + p.fbias[l * 4 + lane];
;           float ls = fminf(v, 0.f) - log1pf(expf(-fabsf(v)));
	s_waitcnt lgkmcnt(3)
	v_add_f32_e32 v2, v2, v7
	v_cmp_lt_i32_e64 s[4:5], 0, v117
	s_and_saveexec_b64 s[64:65], s[4:5]
	s_cbranch_execz .LBB0_619
	v_cmp_ne_u32_e64 s[4:5], 1, v117
	s_and_saveexec_b64 s[38:39], s[4:5]
	s_xor_b64 s[4:5], exec, s[38:39]
	s_cbranch_execz .LBB0_659
	s_waitcnt lgkmcnt(1)
	v_add_f32_e32 v0, v3, v5
	s_waitcnt lgkmcnt(0)
	v_add_f32_e32 v1, v4, v6
	v_cndmask_b32_e32 v2, v1, v0, vcc
